# RG-LRU gate GEMM epilogue: merge the two 8-byte column halves into one 16-byte store per row (half the store instructions)
# baseline (speedup 1.0000x reference)
; #define PG8_STAGE(bufoff, gbase, voff) do { _Pragma("unroll") for (int _i = 0; _i < 2; ++_i) \
;         __builtin_amdgcn_global_load_lds((const unsigned*)((const char*)(gbase) + (voff)[_i]), (PG8_LAS unsigned*)(lds + (bufoff) + ldsw + _i * 8192), 16, 0, 0); } while (0)
; #define PG8_LDA(dst, b, h) do { _Pragma("unroll") for (int m = 0; m < 4; ++m) _Pragma("unroll") for (int k = 0; k < 2; ++k) dst[m][k] = *(const PG8_LAS bf16x8*)(lds + PG8_SA(b, h) + aoff + m * 2048 + k * 1024); } while (0)
; #define PG8_LDB(dst, b, h) do { _Pragma("unroll") for (int n = 0; n < 2; ++n) _Pragma("unroll") for (int k = 0; k < 2; ++k) dst[n][k] = *(const PG8_LAS bf16x8*)(lds + PG8_SB(b, h) + boff + n * 2048 + k * 1024); } while (0)
; #define PG8_MMA(ai, bj, At, Bt) do { __builtin_amdgcn_s_setprio(1); _Pragma("unroll") for (int m = 0; m < 4; ++m) _Pragma("unroll") for (int n = 0; n < 2; ++n) _Pragma("unroll") for (int k = 0; k < 2; ++k) \
;         acc[ai][bj][m][n] = __builtin_amdgcn_mfma_f32_16x16x32_bf16(Bt[n][k], At[m][k], acc[ai][bj][m][n], 0, 0, 0); __builtin_amdgcn_s_setprio(0); } while (0)
; #define PG8_WAIT_L(n) asm volatile("s_waitcnt lgkmcnt(" #n ")" ::: "memory")
; #define PG8_BAR __builtin_amdgcn_s_barrier()
; #define PG8_SCHED __builtin_amdgcn_sched_barrier(0)
; template <class Epi, class Sched>
; __device__ __forceinline__ void gemm_phase(PG8_LAS unsigned char* lds, const Gemm g, const Sched& S, const Epi& E) {
;     ...
;             PG8_LDB(B0, 0, 0); PG8_SCHED; PG8_LDA(At, 0, 0); PG8_STAGE(PG8_SA(1, 1), a1 + hstepA, voffA);
;             PG8_WAIT_L(8); PG8_BAR; PG8_WAIT_L(0); PG8_MMA(0, 0, At, B0); PG8_BAR; PG8_SCHED;
;             PG8_LDB(B1, 0, 1); PG8_STAGE(PG8_SB(0, 0), b2, voffB);
;             PG8_BAR; PG8_WAIT_L(0); PG8_MMA(0, 1, At, B1); PG8_BAR;
;             PG8_LDA(At, 0, 1); PG8_STAGE(PG8_SA(0, 0), a2, voffA);
;             PG8_BAR; PG8_WAIT_L(0); PG8_MMA(1, 0, At, B0); PG8_BAR; PG8_SCHED;
.LBB0_936:
	ds_read_b128 v[2:5], v191
	ds_read_b128 v[6:9], v191 offset:1024
	ds_read_b128 v[10:13], v191 offset:2048
	ds_read_b128 v[14:17], v191 offset:3072
	s_ashr_i32 s31, s30, 31
	s_lshl_b64 s[36:37], s[30:31], 17
	s_add_u32 s36, s43, s36
	s_addc_u32 s37, s44, s37
	s_and_b64 s[8:9], s[8:9], exec
	s_cselect_b32 s9, s37, s41
	s_cselect_b32 s8, s36, s40
	s_add_u32 s66, s38, 0xb0080
	s_addc_u32 s67, s39, 0
	s_add_i32 s71, s47, 0xc000
	v_lshl_add_u64 v[50:51], s[66:67], 0, v[142:143]
	s_mov_b32 m0, s71
	s_add_i32 s31, s47, 0xe000
	ds_read_b128 v[18:21], v192
	ds_read_b128 v[22:25], v192 offset:1024
	ds_read_b128 v[26:29], v192 offset:2048
	ds_read_b128 v[30:33], v192 offset:3072
	ds_read_b128 v[34:37], v192 offset:4096
	ds_read_b128 v[38:41], v192 offset:5120
	ds_read_b128 v[42:45], v192 offset:6144
	ds_read_b128 v[46:49], v192 offset:7168
	global_load_lds_dwordx4 v[50:51], off
	v_lshl_add_u64 v[50:51], s[66:67], 0, v[146:147]
	s_mov_b32 m0, s31
	s_nop 0
	global_load_lds_dwordx4 v[50:51], off
	s_waitcnt lgkmcnt(8)
	s_barrier
	s_waitcnt lgkmcnt(0)
	s_setprio 1
	s_waitcnt lgkmcnt(0)
	v_mfma_f32_16x16x32_bf16 v[50:53], v[2:5], v[18:21], 0
	v_mfma_f32_16x16x32_bf16 v[54:57], v[10:13], v[18:21], 0
	v_mfma_f32_16x16x32_bf16 v[58:61], v[2:5], v[26:29], 0
	v_mfma_f32_16x16x32_bf16 v[62:65], v[10:13], v[26:29], 0
	v_mfma_f32_16x16x32_bf16 v[66:69], v[2:5], v[34:37], 0
	v_mfma_f32_16x16x32_bf16 v[70:73], v[10:13], v[34:37], 0
	v_mfma_f32_16x16x32_bf16 v[74:77], v[2:5], v[42:45], 0
	v_mfma_f32_16x16x32_bf16 v[78:81], v[10:13], v[42:45], 0
	v_mfma_f32_16x16x32_bf16 v[50:53], v[6:9], v[22:25], v[50:53]
	v_mfma_f32_16x16x32_bf16 v[54:57], v[14:17], v[22:25], v[54:57]
	v_mfma_f32_16x16x32_bf16 v[58:61], v[6:9], v[30:33], v[58:61]
	v_mfma_f32_16x16x32_bf16 v[62:65], v[14:17], v[30:33], v[62:65]
	v_mfma_f32_16x16x32_bf16 v[66:69], v[6:9], v[38:41], v[66:69]
	v_mfma_f32_16x16x32_bf16 v[70:73], v[14:17], v[38:41], v[70:73]
	v_mfma_f32_16x16x32_bf16 v[74:77], v[6:9], v[46:49], v[74:77]
	v_mfma_f32_16x16x32_bf16 v[78:81], v[14:17], v[46:49], v[78:81]
	s_setprio 0
	s_barrier
	v_lshl_add_u64 v[218:219], s[40:41], 0, v[144:145]
	s_add_i32 s68, s57, s45
	v_lshl_add_u64 v[98:99], v[218:219], 0, s[24:25]
	s_mov_b32 m0, s68
	v_lshl_add_u64 v[220:221], s[40:41], 0, v[148:149]
	s_add_i32 s66, s68, 0x2000
	ds_read_b128 v[82:85], v193
	ds_read_b128 v[86:89], v193 offset:1024
	ds_read_b128 v[90:93], v193 offset:2048
	ds_read_b128 v[94:97], v193 offset:3072
	global_load_lds_dwordx4 v[98:99], off
	v_lshl_add_u64 v[98:99], v[220:221], 0, s[24:25]
	s_mov_b32 m0, s66
	s_nop 0
	global_load_lds_dwordx4 v[98:99], off
	s_barrier
	s_waitcnt lgkmcnt(0)
	s_setprio 1
	s_waitcnt lgkmcnt(0)
	v_mfma_f32_16x16x32_bf16 v[98:101], v[82:85], v[18:21], 0
	v_mfma_f32_16x16x32_bf16 v[18:21], v[90:93], v[18:21], 0
	v_mfma_f32_16x16x32_bf16 v[98:101], v[86:89], v[22:25], v[98:101]
	v_mfma_f32_16x16x32_bf16 v[18:21], v[94:97], v[22:25], v[18:21]
	v_mfma_f32_16x16x32_bf16 v[22:25], v[82:85], v[26:29], 0
	v_mfma_f32_16x16x32_bf16 v[26:29], v[90:93], v[26:29], 0
	v_mfma_f32_16x16x32_bf16 v[22:25], v[86:89], v[30:33], v[22:25]
	v_mfma_f32_16x16x32_bf16 v[26:29], v[94:97], v[30:33], v[26:29]
	v_mfma_f32_16x16x32_bf16 v[30:33], v[82:85], v[34:37], 0
	v_mfma_f32_16x16x32_bf16 v[34:37], v[90:93], v[34:37], 0
	v_mfma_f32_16x16x32_bf16 v[30:33], v[86:89], v[38:41], v[30:33]
	v_mfma_f32_16x16x32_bf16 v[34:37], v[94:97], v[38:41], v[34:37]
	v_mfma_f32_16x16x32_bf16 v[38:41], v[82:85], v[42:45], 0
	v_mfma_f32_16x16x32_bf16 v[42:45], v[90:93], v[42:45], 0
	v_mfma_f32_16x16x32_bf16 v[38:41], v[86:89], v[46:49], v[38:41]
	v_mfma_f32_16x16x32_bf16 v[42:45], v[94:97], v[46:49], v[42:45]
	s_setprio 0
	v_lshl_add_u64 v[222:223], s[38:39], 0, v[142:143]
	s_mov_b32 m0, s47
	v_lshl_add_u64 v[130:131], v[222:223], 0, s[24:25]
	v_lshl_add_u64 v[224:225], s[38:39], 0, v[146:147]
	s_barrier
	ds_read_b128 v[46:49], v192 offset:16384
	ds_read_b128 v[102:105], v192 offset:17408
	ds_read_b128 v[106:109], v192 offset:18432
	ds_read_b128 v[110:113], v192 offset:19456
	ds_read_b128 v[114:117], v192 offset:20480
	ds_read_b128 v[118:121], v192 offset:21504
	ds_read_b128 v[122:125], v192 offset:22528
	ds_read_b128 v[126:129], v192 offset:23552
	global_load_lds_dwordx4 v[130:131], off
	v_lshl_add_u64 v[130:131], v[224:225], 0, s[24:25]
	s_mov_b32 m0, s48
	s_nop 0
	global_load_lds_dwordx4 v[130:131], off
	s_barrier
	s_waitcnt lgkmcnt(0)
	s_setprio 1
	s_waitcnt lgkmcnt(0)
	v_mfma_f32_16x16x32_bf16 v[130:133], v[2:5], v[46:49], 0
	v_mfma_f32_16x16x32_bf16 v[138:141], v[2:5], v[106:109], 0
	v_mfma_f32_16x16x32_bf16 v[164:167], v[2:5], v[114:117], 0
	v_mfma_f32_16x16x32_bf16 v[2:5], v[2:5], v[122:125], 0
	v_mfma_f32_16x16x32_bf16 v[130:133], v[6:9], v[102:105], v[130:133]
	v_mfma_f32_16x16x32_bf16 v[134:137], v[10:13], v[46:49], 0
	v_mfma_f32_16x16x32_bf16 v[138:141], v[6:9], v[110:113], v[138:141]
	v_mfma_f32_16x16x32_bf16 v[160:163], v[10:13], v[106:109], 0
	v_mfma_f32_16x16x32_bf16 v[164:167], v[6:9], v[118:121], v[164:167]
	v_mfma_f32_16x16x32_bf16 v[168:171], v[10:13], v[114:117], 0
	v_mfma_f32_16x16x32_bf16 v[2:5], v[6:9], v[126:129], v[2:5]
	v_mfma_f32_16x16x32_bf16 v[6:9], v[10:13], v[122:125], 0
	v_mfma_f32_16x16x32_bf16 v[134:137], v[14:17], v[102:105], v[134:137]
	v_mfma_f32_16x16x32_bf16 v[160:163], v[14:17], v[110:113], v[160:163]
	v_mfma_f32_16x16x32_bf16 v[168:171], v[14:17], v[118:121], v[168:171]
	v_mfma_f32_16x16x32_bf16 v[6:9], v[14:17], v[126:129], v[6:9]
	s_setprio 0
	s_barrier
; #define PG8_STAGE(bufoff, gbase, voff) do { _Pragma("unroll") for (int _i = 0; _i < 2; ++_i) \
;         __builtin_amdgcn_global_load_lds((const unsigned*)((const char*)(gbase) + (voff)[_i]), (PG8_LAS unsigned*)(lds + (bufoff) + ldsw + _i * 8192), 16, 0, 0); } while (0)
; #define PG8_LDA(dst, b, h) do { _Pragma("unroll") for (int m = 0; m < 4; ++m) _Pragma("unroll") for (int k = 0; k < 2; ++k) dst[m][k] = *(const PG8_LAS bf16x8*)(lds + PG8_SA(b, h) + aoff + m * 2048 + k * 1024); } while (0)
; #define PG8_LDB(dst, b, h) do { _Pragma("unroll") for (int n = 0; n < 2; ++n) _Pragma("unroll") for (int k = 0; k < 2; ++k) dst[n][k] = *(const PG8_LAS bf16x8*)(lds + PG8_SB(b, h) + boff + n * 2048 + k * 1024); } while (0)
; #define PG8_MMA(ai, bj, At, Bt) do { __builtin_amdgcn_s_setprio(1); _Pragma("unroll") for (int m = 0; m < 4; ++m) _Pragma("unroll") for (int n = 0; n < 2; ++n) _Pragma("unroll") for (int k = 0; k < 2; ++k) \
;         acc[ai][bj][m][n] = __builtin_amdgcn_mfma_f32_16x16x32_bf16(Bt[n][k], At[m][k], acc[ai][bj][m][n], 0, 0, 0); __builtin_amdgcn_s_setprio(0); } while (0)
; #define PG8_WAIT_V(n) asm volatile("s_waitcnt vmcnt(" #n ")" ::: "memory")
; #define PG8_WAIT_L(n) asm volatile("s_waitcnt lgkmcnt(" #n ")" ::: "memory")
; #define PG8_BAR __builtin_amdgcn_s_barrier()
; #define PG8_SCHED __builtin_amdgcn_sched_barrier(0)
; template <class Epi, class Sched>
; __device__ __forceinline__ void gemm_phase(PG8_LAS unsigned char* lds, const Gemm g, const Sched& S, const Epi& E) {
;     ...
;             PG8_STAGE(PG8_SB(0, 1), b2 + hstepB, voffB);
;             PG8_WAIT_V(6); PG8_BAR; PG8_MMA(1, 1, At, B1); PG8_BAR;
;             PG8_LDB(B0, 1, 0); PG8_SCHED; PG8_LDA(At, 1, 0); PG8_STAGE(PG8_SA(0, 1), a2 + hstepA, voffA);
;             PG8_WAIT_L(8); PG8_BAR; PG8_WAIT_L(0); PG8_MMA(0, 0, At, B0); PG8_BAR; PG8_SCHED;
;             PG8_LDB(B1, 1, 1); PG8_STAGE(PG8_SB(1, 0), b3, voffB);
;             PG8_BAR; PG8_WAIT_L(0); PG8_MMA(0, 1, At, B1); PG8_BAR;
	s_add_u32 s72, s40, 0x10100
	s_addc_u32 s73, s41, 0
	s_add_i32 s69, s58, s45
	v_lshl_add_u64 v[10:11], s[72:73], 0, v[144:145]
	s_mov_b32 m0, s69
	s_add_i32 s67, s69, 0x2000
	global_load_lds_dwordx4 v[10:11], off
	v_lshl_add_u64 v[10:11], s[72:73], 0, v[148:149]
	s_mov_b32 m0, s67
	s_nop 0
	global_load_lds_dwordx4 v[10:11], off
	s_waitcnt vmcnt(6)
	s_barrier
	s_setprio 1
	v_mfma_f32_16x16x32_bf16 v[10:13], v[82:85], v[46:49], 0
	v_mfma_f32_16x16x32_bf16 v[14:17], v[90:93], v[46:49], 0
	v_mfma_f32_16x16x32_bf16 v[10:13], v[86:89], v[102:105], v[10:13]
	v_mfma_f32_16x16x32_bf16 v[14:17], v[94:97], v[102:105], v[14:17]
	v_mfma_f32_16x16x32_bf16 v[46:49], v[82:85], v[106:109], 0
	v_mfma_f32_16x16x32_bf16 v[102:105], v[90:93], v[106:109], 0
	v_mfma_f32_16x16x32_bf16 v[106:109], v[82:85], v[114:117], 0
	v_mfma_f32_16x16x32_bf16 v[82:85], v[82:85], v[122:125], 0
	v_mfma_f32_16x16x32_bf16 v[46:49], v[86:89], v[110:113], v[46:49]
	v_mfma_f32_16x16x32_bf16 v[102:105], v[94:97], v[110:113], v[102:105]
	v_mfma_f32_16x16x32_bf16 v[106:109], v[86:89], v[118:121], v[106:109]
	v_mfma_f32_16x16x32_bf16 v[110:113], v[90:93], v[114:117], 0
	v_mfma_f32_16x16x32_bf16 v[82:85], v[86:89], v[126:129], v[82:85]
	v_mfma_f32_16x16x32_bf16 v[86:89], v[90:93], v[122:125], 0
	v_mfma_f32_16x16x32_bf16 v[110:113], v[94:97], v[118:121], v[110:113]
	v_mfma_f32_16x16x32_bf16 v[86:89], v[94:97], v[126:129], v[86:89]
	s_setprio 0
	s_add_i32 s70, 0, 0x18000
	v_add_u32_e32 v238, s70, v189
	s_barrier
	ds_read_b128 v[90:93], v238
	ds_read_b128 v[94:97], v238 offset:1024
	ds_read_b128 v[114:117], v238 offset:2048
	ds_read_b128 v[118:121], v238 offset:3072
	s_add_u32 s72, s38, 0xb0100
	s_addc_u32 s73, s39, 0
	s_mov_b32 m0, s49
	v_lshl_add_u64 v[202:203], s[72:73], 0, v[142:143]
	ds_read_b128 v[122:125], v192 offset:32768
	ds_read_b128 v[126:129], v192 offset:33792
	ds_read_b128 v[172:175], v192 offset:34816
	ds_read_b128 v[176:179], v192 offset:35840
	ds_read_b128 v[180:183], v192 offset:36864
	ds_read_b128 v[184:187], v192 offset:37888
	ds_read_b128 v[194:197], v192 offset:38912
	ds_read_b128 v[198:201], v192 offset:39936
	global_load_lds_dwordx4 v[202:203], off
	v_lshl_add_u64 v[202:203], s[72:73], 0, v[146:147]
	s_mov_b32 m0, s50
	s_nop 0
	global_load_lds_dwordx4 v[202:203], off
	s_waitcnt lgkmcnt(8)
	s_barrier
	s_waitcnt lgkmcnt(0)
	s_setprio 1
	s_waitcnt lgkmcnt(0)
	v_mfma_f32_16x16x32_bf16 v[50:53], v[90:93], v[122:125], v[50:53]
	v_mfma_f32_16x16x32_bf16 v[54:57], v[114:117], v[122:125], v[54:57]
	v_mfma_f32_16x16x32_bf16 v[58:61], v[90:93], v[172:175], v[58:61]
	v_mfma_f32_16x16x32_bf16 v[62:65], v[114:117], v[172:175], v[62:65]
	v_mfma_f32_16x16x32_bf16 v[66:69], v[90:93], v[180:183], v[66:69]
	v_mfma_f32_16x16x32_bf16 v[70:73], v[114:117], v[180:183], v[70:73]
	v_mfma_f32_16x16x32_bf16 v[74:77], v[90:93], v[194:197], v[74:77]
	v_mfma_f32_16x16x32_bf16 v[78:81], v[114:117], v[194:197], v[78:81]
	v_mfma_f32_16x16x32_bf16 v[50:53], v[94:97], v[126:129], v[50:53]
	v_mfma_f32_16x16x32_bf16 v[54:57], v[118:121], v[126:129], v[54:57]
	v_mfma_f32_16x16x32_bf16 v[58:61], v[94:97], v[176:179], v[58:61]
	v_mfma_f32_16x16x32_bf16 v[62:65], v[118:121], v[176:179], v[62:65]
	v_mfma_f32_16x16x32_bf16 v[66:69], v[94:97], v[184:187], v[66:69]
	v_mfma_f32_16x16x32_bf16 v[70:73], v[118:121], v[184:187], v[70:73]
	v_mfma_f32_16x16x32_bf16 v[74:77], v[94:97], v[198:201], v[74:77]
	v_mfma_f32_16x16x32_bf16 v[78:81], v[118:121], v[198:201], v[78:81]
	s_setprio 0
	s_barrier
	s_add_i32 s73, 0, 0x1c000
	s_add_i32 s72, s70, s45
	v_add_u32_e32 v246, s73, v189
	v_lshl_add_u64 v[218:219], v[218:219], 0, s[26:27]
	s_mov_b32 m0, s72
	s_add_i32 s70, s72, 0x2000
	ds_read_b128 v[202:205], v246
	ds_read_b128 v[206:209], v246 offset:1024
	ds_read_b128 v[210:213], v246 offset:2048
	ds_read_b128 v[214:217], v246 offset:3072
	global_load_lds_dwordx4 v[218:219], off
	v_lshl_add_u64 v[218:219], v[220:221], 0, s[26:27]
	s_mov_b32 m0, s70
	s_nop 0
	global_load_lds_dwordx4 v[218:219], off
	s_barrier
	s_waitcnt lgkmcnt(0)
	s_setprio 1
	s_waitcnt lgkmcnt(0)
	v_mfma_f32_16x16x32_bf16 v[98:101], v[202:205], v[122:125], v[98:101]
	v_mfma_f32_16x16x32_bf16 v[18:21], v[210:213], v[122:125], v[18:21]
	v_mfma_f32_16x16x32_bf16 v[22:25], v[202:205], v[172:175], v[22:25]
	v_mfma_f32_16x16x32_bf16 v[26:29], v[210:213], v[172:175], v[26:29]
	v_mfma_f32_16x16x32_bf16 v[30:33], v[202:205], v[180:183], v[30:33]
	v_mfma_f32_16x16x32_bf16 v[34:37], v[210:213], v[180:183], v[34:37]
	v_mfma_f32_16x16x32_bf16 v[38:41], v[202:205], v[194:197], v[38:41]
	v_mfma_f32_16x16x32_bf16 v[42:45], v[210:213], v[194:197], v[42:45]
	v_mfma_f32_16x16x32_bf16 v[98:101], v[206:209], v[126:129], v[98:101]
	v_mfma_f32_16x16x32_bf16 v[18:21], v[214:217], v[126:129], v[18:21]
	v_mfma_f32_16x16x32_bf16 v[22:25], v[206:209], v[176:179], v[22:25]
	v_mfma_f32_16x16x32_bf16 v[26:29], v[214:217], v[176:179], v[26:29]
	v_mfma_f32_16x16x32_bf16 v[30:33], v[206:209], v[184:187], v[30:33]
	v_mfma_f32_16x16x32_bf16 v[34:37], v[214:217], v[184:187], v[34:37]
	v_mfma_f32_16x16x32_bf16 v[38:41], v[206:209], v[198:201], v[38:41]
	v_mfma_f32_16x16x32_bf16 v[42:45], v[214:217], v[198:201], v[42:45]
	s_setprio 0
	s_mov_b32 m0, s53
	v_lshl_add_u64 v[218:219], v[222:223], 0, s[26:27]
	s_barrier
	ds_read_b128 v[122:125], v192 offset:49152
	ds_read_b128 v[126:129], v192 offset:50176
	ds_read_b128 v[172:175], v192 offset:51200
	ds_read_b128 v[176:179], v192 offset:52224
	ds_read_b128 v[180:183], v192 offset:53248
	ds_read_b128 v[184:187], v192 offset:54272
	ds_read_b128 v[194:197], v192 offset:55296
	ds_read_b128 v[198:201], v192 offset:56320
	global_load_lds_dwordx4 v[218:219], off
	v_lshl_add_u64 v[218:219], v[224:225], 0, s[26:27]
	s_mov_b32 m0, s54
	s_nop 0
	global_load_lds_dwordx4 v[218:219], off
	s_barrier
; #define PG8_STAGE(bufoff, gbase, voff) do { _Pragma("unroll") for (int _i = 0; _i < 2; ++_i) \
;         __builtin_amdgcn_global_load_lds((const unsigned*)((const char*)(gbase) + (voff)[_i]), (PG8_LAS unsigned*)(lds + (bufoff) + ldsw + _i * 8192), 16, 0, 0); } while (0)
; #define PG8_LDA(dst, b, h) do { _Pragma("unroll") for (int m = 0; m < 4; ++m) _Pragma("unroll") for (int k = 0; k < 2; ++k) dst[m][k] = *(const PG8_LAS bf16x8*)(lds + PG8_SA(b, h) + aoff + m * 2048 + k * 1024); } while (0)
; #define PG8_LDB(dst, b, h) do { _Pragma("unroll") for (int n = 0; n < 2; ++n) _Pragma("unroll") for (int k = 0; k < 2; ++k) dst[n][k] = *(const PG8_LAS bf16x8*)(lds + PG8_SB(b, h) + boff + n * 2048 + k * 1024); } while (0)
; #define PG8_WAIT_V(n) asm volatile("s_waitcnt vmcnt(" #n ")" ::: "memory")
; #define PG8_WAIT_L(n) asm volatile("s_waitcnt lgkmcnt(" #n ")" ::: "memory")
; #define PG8_BAR __builtin_amdgcn_s_barrier()
; #define PG8_SCHED __builtin_amdgcn_sched_barrier(0)
; template <class Epi, class Sched>
; __device__ __forceinline__ void gemm_phase(PG8_LAS unsigned char* lds, const Gemm g, const Sched& S, const Epi& E) {
;     ...
;             PG8_LDB(B0, 0, 0); PG8_SCHED; PG8_LDA(At, 0, 0); PG8_STAGE(PG8_SA(1, 1), a1 + hstepA, voffA);
;             PG8_WAIT_L(8); PG8_BAR; PG8_WAIT_L(0); PG8_MMA(0, 0, At, B0); PG8_BAR; PG8_SCHED;
;             PG8_LDB(B1, 0, 1); PG8_STAGE(PG8_SB(0, 0), b2, voffB);
;             PG8_BAR; PG8_WAIT_L(0); PG8_MMA(0, 1, At, B1); PG8_BAR;
;             PG8_LDA(At, 0, 1); PG8_STAGE(PG8_SA(0, 0), a2, voffA);
;             PG8_BAR; PG8_WAIT_L(0); PG8_MMA(1, 0, At, B0); PG8_BAR; PG8_SCHED;
;             PG8_STAGE(PG8_SB(0, 1), b2 + hstepB, voffB);
;             PG8_WAIT_V(6); PG8_BAR; PG8_MMA(1, 1, At, B1); PG8_BAR;
;             PG8_LDB(B0, 1, 0); PG8_SCHED; PG8_LDA(At, 1, 0); PG8_STAGE(PG8_SA(0, 1), a2 + hstepA, voffA);
;             PG8_WAIT_L(8); PG8_BAR; PG8_WAIT_L(0); PG8_MMA(0, 0, At, B0); PG8_BAR; PG8_SCHED;
;             PG8_LDB(B1, 1, 1); PG8_STAGE(PG8_SB(1, 0), b3, voffB);
;             PG8_BAR; PG8_WAIT_L(0); PG8_MMA(0, 1, At, B1); PG8_BAR;
;             PG8_LDA(At, 1, 1); PG8_STAGE(PG8_SA(1, 0), a3, voffA);
;             PG8_BAR; PG8_WAIT_L(0); PG8_MMA(1, 0, At, B0); PG8_BAR; PG8_SCHED;
;             PG8_STAGE(PG8_SB(1, 1), b3 + hstepB, voffB);
;             PG8_WAIT_V(6); PG8_BAR; PG8_MMA(1, 1, At, B1); PG8_BAR;
	s_waitcnt lgkmcnt(0)
	s_setprio 1
	s_waitcnt lgkmcnt(0)
	v_mfma_f32_16x16x32_bf16 v[130:133], v[90:93], v[122:125], v[130:133]
	v_mfma_f32_16x16x32_bf16 v[134:137], v[114:117], v[122:125], v[134:137]
	v_mfma_f32_16x16x32_bf16 v[138:141], v[90:93], v[172:175], v[138:141]
	v_mfma_f32_16x16x32_bf16 v[160:163], v[114:117], v[172:175], v[160:163]
	v_mfma_f32_16x16x32_bf16 v[164:167], v[90:93], v[180:183], v[164:167]
	v_mfma_f32_16x16x32_bf16 v[168:171], v[114:117], v[180:183], v[168:171]
	v_mfma_f32_16x16x32_bf16 v[2:5], v[90:93], v[194:197], v[2:5]
	v_mfma_f32_16x16x32_bf16 v[6:9], v[114:117], v[194:197], v[6:9]
	v_mfma_f32_16x16x32_bf16 v[130:133], v[94:97], v[126:129], v[130:133]
	v_mfma_f32_16x16x32_bf16 v[134:137], v[118:121], v[126:129], v[134:137]
	v_mfma_f32_16x16x32_bf16 v[138:141], v[94:97], v[176:179], v[138:141]
	v_mfma_f32_16x16x32_bf16 v[160:163], v[118:121], v[176:179], v[160:163]
	v_mfma_f32_16x16x32_bf16 v[164:167], v[94:97], v[184:187], v[164:167]
	v_mfma_f32_16x16x32_bf16 v[168:171], v[118:121], v[184:187], v[168:171]
	v_mfma_f32_16x16x32_bf16 v[2:5], v[94:97], v[198:201], v[2:5]
	v_mfma_f32_16x16x32_bf16 v[6:9], v[118:121], v[198:201], v[6:9]
	s_setprio 0
	s_barrier
	s_add_u32 s78, s40, 0x10180
	s_addc_u32 s79, s41, 0
	s_add_i32 s41, s73, s45
	v_lshl_add_u64 v[90:91], s[78:79], 0, v[144:145]
	s_mov_b32 m0, s41
	s_add_i32 s40, s41, 0x2000
	global_load_lds_dwordx4 v[90:91], off
	v_lshl_add_u64 v[90:91], s[78:79], 0, v[148:149]
	s_mov_b32 m0, s40
	s_nop 0
	global_load_lds_dwordx4 v[90:91], off
	s_waitcnt vmcnt(6)
	s_barrier
	s_setprio 1
	v_mfma_f32_16x16x32_bf16 v[10:13], v[202:205], v[122:125], v[10:13]
	v_mfma_f32_16x16x32_bf16 v[14:17], v[210:213], v[122:125], v[14:17]
	v_mfma_f32_16x16x32_bf16 v[46:49], v[202:205], v[172:175], v[46:49]
	v_mfma_f32_16x16x32_bf16 v[90:93], v[210:213], v[172:175], v[102:105]
	v_mfma_f32_16x16x32_bf16 v[94:97], v[202:205], v[180:183], v[106:109]
	v_mfma_f32_16x16x32_bf16 v[102:105], v[210:213], v[180:183], v[110:113]
	v_mfma_f32_16x16x32_bf16 v[82:85], v[202:205], v[194:197], v[82:85]
	v_mfma_f32_16x16x32_bf16 v[86:89], v[210:213], v[194:197], v[86:89]
	v_mfma_f32_16x16x32_bf16 v[10:13], v[206:209], v[126:129], v[10:13]
	v_mfma_f32_16x16x32_bf16 v[14:17], v[214:217], v[126:129], v[14:17]
	v_mfma_f32_16x16x32_bf16 v[46:49], v[206:209], v[176:179], v[46:49]
	v_mfma_f32_16x16x32_bf16 v[90:93], v[214:217], v[176:179], v[90:93]
	v_mfma_f32_16x16x32_bf16 v[94:97], v[206:209], v[184:187], v[94:97]
	v_mfma_f32_16x16x32_bf16 v[102:105], v[214:217], v[184:187], v[102:105]
	v_mfma_f32_16x16x32_bf16 v[82:85], v[206:209], v[198:201], v[82:85]
	v_mfma_f32_16x16x32_bf16 v[86:89], v[214:217], v[198:201], v[86:89]
	s_setprio 0
	s_barrier
	ds_read_b128 v[106:109], v191
	ds_read_b128 v[110:113], v191 offset:1024
	ds_read_b128 v[114:117], v191 offset:2048
	ds_read_b128 v[118:121], v191 offset:3072
	s_add_u32 s38, s38, 0xb0180
	s_addc_u32 s39, s39, 0
	s_mov_b32 m0, s71
	v_lshl_add_u64 v[202:203], s[38:39], 0, v[142:143]
	ds_read_b128 v[122:125], v192
	ds_read_b128 v[126:129], v192 offset:1024
	ds_read_b128 v[172:175], v192 offset:2048
	ds_read_b128 v[176:179], v192 offset:3072
	ds_read_b128 v[180:183], v192 offset:4096
	ds_read_b128 v[184:187], v192 offset:5120
	ds_read_b128 v[194:197], v192 offset:6144
	ds_read_b128 v[198:201], v192 offset:7168
	global_load_lds_dwordx4 v[202:203], off
	v_lshl_add_u64 v[202:203], s[38:39], 0, v[146:147]
	s_mov_b32 m0, s31
	s_nop 0
	global_load_lds_dwordx4 v[202:203], off
	s_waitcnt lgkmcnt(8)
	s_barrier
	s_waitcnt lgkmcnt(0)
	s_setprio 1
	s_waitcnt lgkmcnt(0)
	v_mfma_f32_16x16x32_bf16 v[58:61], v[106:109], v[172:175], v[58:61]
	v_mfma_f32_16x16x32_bf16 v[202:205], v[110:113], v[176:179], v[58:61]
	v_mfma_f32_16x16x32_bf16 v[58:61], v[114:117], v[172:175], v[62:65]
	v_mfma_f32_16x16x32_bf16 v[62:65], v[118:121], v[176:179], v[58:61]
	v_mfma_f32_16x16x32_bf16 v[58:61], v[106:109], v[180:183], v[66:69]
	v_mfma_f32_16x16x32_bf16 v[66:69], v[110:113], v[184:187], v[58:61]
	v_mfma_f32_16x16x32_bf16 v[58:61], v[114:117], v[180:183], v[70:73]
	v_mfma_f32_16x16x32_bf16 v[70:73], v[118:121], v[184:187], v[58:61]
	v_mfma_f32_16x16x32_bf16 v[58:61], v[106:109], v[194:197], v[74:77]
	v_mfma_f32_16x16x32_bf16 v[50:53], v[106:109], v[122:125], v[50:53]
	v_mfma_f32_16x16x32_bf16 v[54:57], v[114:117], v[122:125], v[54:57]
	v_mfma_f32_16x16x32_bf16 v[74:77], v[110:113], v[198:201], v[58:61]
	v_mfma_f32_16x16x32_bf16 v[58:61], v[114:117], v[194:197], v[78:81]
	v_mfma_f32_16x16x32_bf16 v[50:53], v[110:113], v[126:129], v[50:53]
	v_mfma_f32_16x16x32_bf16 v[54:57], v[118:121], v[126:129], v[54:57]
	v_mfma_f32_16x16x32_bf16 v[78:81], v[118:121], v[198:201], v[58:61]
	s_setprio 0
	s_barrier
	s_mov_b32 m0, s68
	v_lshl_add_u64 v[242:243], s[8:9], 0, v[144:145]
	s_nop 0
	ds_read_b128 v[58:61], v193
	ds_read_b128 v[206:209], v193 offset:1024
	ds_read_b128 v[210:213], v193 offset:2048
	ds_read_b128 v[214:217], v193 offset:3072
	global_load_lds_dwordx4 v[242:243], off
	v_lshl_add_u64 v[244:245], s[8:9], 0, v[148:149]
	s_mov_b32 m0, s66
	s_nop 0
	global_load_lds_dwordx4 v[244:245], off
	s_barrier
; #define PG8_STAGE(bufoff, gbase, voff) do { _Pragma("unroll") for (int _i = 0; _i < 2; ++_i) \
;         __builtin_amdgcn_global_load_lds((const unsigned*)((const char*)(gbase) + (voff)[_i]), (PG8_LAS unsigned*)(lds + (bufoff) + ldsw + _i * 8192), 16, 0, 0); } while (0)
; #define PG8_LDA(dst, b, h) do { _Pragma("unroll") for (int m = 0; m < 4; ++m) _Pragma("unroll") for (int k = 0; k < 2; ++k) dst[m][k] = *(const PG8_LAS bf16x8*)(lds + PG8_SA(b, h) + aoff + m * 2048 + k * 1024); } while (0)
; #define PG8_LDB(dst, b, h) do { _Pragma("unroll") for (int n = 0; n < 2; ++n) _Pragma("unroll") for (int k = 0; k < 2; ++k) dst[n][k] = *(const PG8_LAS bf16x8*)(lds + PG8_SB(b, h) + boff + n * 2048 + k * 1024); } while (0)
; #define PG8_MMA(ai, bj, At, Bt) do { __builtin_amdgcn_s_setprio(1); _Pragma("unroll") for (int m = 0; m < 4; ++m) _Pragma("unroll") for (int n = 0; n < 2; ++n) _Pragma("unroll") for (int k = 0; k < 2; ++k) \
;         acc[ai][bj][m][n] = __builtin_amdgcn_mfma_f32_16x16x32_bf16(Bt[n][k], At[m][k], acc[ai][bj][m][n], 0, 0, 0); __builtin_amdgcn_s_setprio(0); } while (0)
; #define PG8_WAIT_V(n) asm volatile("s_waitcnt vmcnt(" #n ")" ::: "memory")
; #define PG8_WAIT_L(n) asm volatile("s_waitcnt lgkmcnt(" #n ")" ::: "memory")
; #define PG8_BAR __builtin_amdgcn_s_barrier()
; #define PG8_SCHED __builtin_amdgcn_sched_barrier(0)
; template <class Epi, class Sched>
; __device__ __forceinline__ void gemm_phase(PG8_LAS unsigned char* lds, const Gemm g, const Sched& S, const Epi& E) {
;     ...
;             PG8_LDB(B1, 0, 1); PG8_STAGE(PG8_SB(0, 0), b2, voffB);
;             PG8_BAR; PG8_WAIT_L(0); PG8_MMA(0, 1, At, B1); PG8_BAR;
;             PG8_LDA(At, 0, 1); PG8_STAGE(PG8_SA(0, 0), a2, voffA);
;             PG8_BAR; PG8_WAIT_L(0); PG8_MMA(1, 0, At, B0); PG8_BAR; PG8_SCHED;
;             PG8_STAGE(PG8_SB(0, 1), b2 + hstepB, voffB);
;             PG8_WAIT_V(6); PG8_BAR; PG8_MMA(1, 1, At, B1); PG8_BAR;
;             PG8_LDB(B0, 1, 0); PG8_SCHED; PG8_LDA(At, 1, 0); PG8_STAGE(PG8_SA(0, 1), a2 + hstepA, voffA);
;             PG8_WAIT_L(8); PG8_BAR; PG8_WAIT_L(0); PG8_MMA(0, 0, At, B0); PG8_BAR; PG8_SCHED;
	s_waitcnt lgkmcnt(0)
	s_setprio 1
	s_waitcnt lgkmcnt(0)
	v_mfma_f32_16x16x32_bf16 v[34:37], v[210:213], v[180:183], v[34:37]
	v_mfma_f32_16x16x32_bf16 v[22:25], v[58:61], v[172:175], v[22:25]
	v_mfma_f32_16x16x32_bf16 v[26:29], v[210:213], v[172:175], v[26:29]
	v_mfma_f32_16x16x32_bf16 v[172:175], v[214:217], v[184:187], v[34:37]
	v_mfma_f32_16x16x32_bf16 v[34:37], v[58:61], v[194:197], v[38:41]
	v_mfma_f32_16x16x32_bf16 v[98:101], v[58:61], v[122:125], v[98:101]
	v_mfma_f32_16x16x32_bf16 v[18:21], v[210:213], v[122:125], v[18:21]
	v_mfma_f32_16x16x32_bf16 v[30:33], v[58:61], v[180:183], v[30:33]
	v_mfma_f32_16x16x32_bf16 v[38:41], v[206:209], v[198:201], v[34:37]
	v_mfma_f32_16x16x32_bf16 v[34:37], v[210:213], v[194:197], v[42:45]
	v_mfma_f32_16x16x32_bf16 v[98:101], v[206:209], v[126:129], v[98:101]
	v_mfma_f32_16x16x32_bf16 v[18:21], v[214:217], v[126:129], v[18:21]
	v_mfma_f32_16x16x32_bf16 v[22:25], v[206:209], v[176:179], v[22:25]
	v_mfma_f32_16x16x32_bf16 v[26:29], v[214:217], v[176:179], v[26:29]
	v_mfma_f32_16x16x32_bf16 v[30:33], v[206:209], v[184:187], v[30:33]
	v_mfma_f32_16x16x32_bf16 v[176:179], v[214:217], v[198:201], v[34:37]
	s_setprio 0
	s_mov_b32 m0, s47
	v_lshl_add_u64 v[250:251], s[34:35], 0, v[142:143]
	s_barrier
	ds_read_b128 v[34:37], v192 offset:16384
	ds_read_b128 v[42:45], v192 offset:17408
	ds_read_b128 v[122:125], v192 offset:18432
	ds_read_b128 v[126:129], v192 offset:19456
	ds_read_b128 v[180:183], v192 offset:20480
	ds_read_b128 v[184:187], v192 offset:21504
	ds_read_b128 v[194:197], v192 offset:22528
	ds_read_b128 v[198:201], v192 offset:23552
	global_load_lds_dwordx4 v[250:251], off
	v_lshl_add_u64 v[252:253], s[34:35], 0, v[146:147]
	s_mov_b32 m0, s48
	s_nop 0
	global_load_lds_dwordx4 v[252:253], off
	s_barrier
	s_waitcnt lgkmcnt(0)
	s_setprio 1
	s_waitcnt lgkmcnt(0)
	v_mfma_f32_16x16x32_bf16 v[130:133], v[106:109], v[34:37], v[130:133]
	v_mfma_f32_16x16x32_bf16 v[218:221], v[110:113], v[42:45], v[130:133]
	v_mfma_f32_16x16x32_bf16 v[130:133], v[114:117], v[34:37], v[134:137]
	v_mfma_f32_16x16x32_bf16 v[222:225], v[118:121], v[42:45], v[130:133]
	v_mfma_f32_16x16x32_bf16 v[130:133], v[106:109], v[122:125], v[138:141]
	v_mfma_f32_16x16x32_bf16 v[226:229], v[110:113], v[126:129], v[130:133]
	v_mfma_f32_16x16x32_bf16 v[130:133], v[114:117], v[122:125], v[160:163]
	v_mfma_f32_16x16x32_bf16 v[160:163], v[118:121], v[126:129], v[130:133]
	v_mfma_f32_16x16x32_bf16 v[130:133], v[106:109], v[180:183], v[164:167]
	v_mfma_f32_16x16x32_bf16 v[164:167], v[110:113], v[184:187], v[130:133]
	v_mfma_f32_16x16x32_bf16 v[130:133], v[114:117], v[180:183], v[168:171]
	v_mfma_f32_16x16x32_bf16 v[2:5], v[106:109], v[194:197], v[2:5]
	v_mfma_f32_16x16x32_bf16 v[6:9], v[114:117], v[194:197], v[6:9]
	v_mfma_f32_16x16x32_bf16 v[168:171], v[118:121], v[184:187], v[130:133]
	v_mfma_f32_16x16x32_bf16 v[2:5], v[110:113], v[198:201], v[2:5]
	v_mfma_f32_16x16x32_bf16 v[6:9], v[118:121], v[198:201], v[6:9]
	s_setprio 0
	s_barrier
	s_add_u32 s38, s8, 0x10000
	s_addc_u32 s39, s9, 0
	s_mov_b32 m0, s69
	v_lshl_add_u64 v[106:107], s[38:39], 0, v[144:145]
	global_load_lds_dwordx4 v[106:107], off
	v_lshl_add_u64 v[106:107], s[38:39], 0, v[148:149]
	s_mov_b32 m0, s67
	s_nop 0
	global_load_lds_dwordx4 v[106:107], off
	s_waitcnt vmcnt(6)
	s_barrier
	s_setprio 1
	v_mfma_f32_16x16x32_bf16 v[10:13], v[58:61], v[34:37], v[10:13]
	v_mfma_f32_16x16x32_bf16 v[106:109], v[206:209], v[42:45], v[10:13]
	v_mfma_f32_16x16x32_bf16 v[10:13], v[210:213], v[34:37], v[14:17]
	v_mfma_f32_16x16x32_bf16 v[14:17], v[214:217], v[42:45], v[10:13]
	v_mfma_f32_16x16x32_bf16 v[10:13], v[58:61], v[122:125], v[46:49]
	v_mfma_f32_16x16x32_bf16 v[230:233], v[206:209], v[126:129], v[10:13]
	v_mfma_f32_16x16x32_bf16 v[10:13], v[210:213], v[122:125], v[90:93]
	v_mfma_f32_16x16x32_bf16 v[90:93], v[214:217], v[126:129], v[10:13]
	v_mfma_f32_16x16x32_bf16 v[10:13], v[58:61], v[180:183], v[94:97]
	v_mfma_f32_16x16x32_bf16 v[234:237], v[206:209], v[184:187], v[10:13]
	v_mfma_f32_16x16x32_bf16 v[10:13], v[210:213], v[180:183], v[102:105]
	v_mfma_f32_16x16x32_bf16 v[180:183], v[214:217], v[184:187], v[10:13]
	v_mfma_f32_16x16x32_bf16 v[10:13], v[58:61], v[194:197], v[82:85]
	v_mfma_f32_16x16x32_bf16 v[82:85], v[206:209], v[198:201], v[10:13]
	v_mfma_f32_16x16x32_bf16 v[10:13], v[210:213], v[194:197], v[86:89]
	v_mfma_f32_16x16x32_bf16 v[184:187], v[214:217], v[198:201], v[10:13]
	s_setprio 0
	s_barrier
	ds_read_b128 v[194:197], v238
	ds_read_b128 v[198:201], v238 offset:1024
	ds_read_b128 v[206:209], v238 offset:2048
	ds_read_b128 v[210:213], v238 offset:3072
	s_add_u32 s38, s34, 0xb0000
	s_addc_u32 s39, s35, 0
	s_mov_b32 m0, s49
	v_lshl_add_u64 v[34:35], s[38:39], 0, v[142:143]
	ds_read_b128 v[10:13], v192 offset:32768
	ds_read_b128 v[46:49], v192 offset:33792
	ds_read_b128 v[86:89], v192 offset:34816
	ds_read_b128 v[94:97], v192 offset:35840
	ds_read_b128 v[102:105], v192 offset:36864
	ds_read_b128 v[114:117], v192 offset:37888
	ds_read_b128 v[214:217], v192 offset:38912
	ds_read_b128 v[238:241], v192 offset:39936
	global_load_lds_dwordx4 v[34:35], off
	v_lshl_add_u64 v[34:35], s[38:39], 0, v[146:147]
	s_mov_b32 m0, s50
	s_nop 0
	global_load_lds_dwordx4 v[34:35], off
	s_waitcnt lgkmcnt(8)
	s_barrier
; #define PG8_STAGE(bufoff, gbase, voff) do { _Pragma("unroll") for (int _i = 0; _i < 2; ++_i) \
;         __builtin_amdgcn_global_load_lds((const unsigned*)((const char*)(gbase) + (voff)[_i]), (PG8_LAS unsigned*)(lds + (bufoff) + ldsw + _i * 8192), 16, 0, 0); } while (0)
; #define PG8_LDA(dst, b, h) do { _Pragma("unroll") for (int m = 0; m < 4; ++m) _Pragma("unroll") for (int k = 0; k < 2; ++k) dst[m][k] = *(const PG8_LAS bf16x8*)(lds + PG8_SA(b, h) + aoff + m * 2048 + k * 1024); } while (0)
; #define PG8_LDB(dst, b, h) do { _Pragma("unroll") for (int n = 0; n < 2; ++n) _Pragma("unroll") for (int k = 0; k < 2; ++k) dst[n][k] = *(const PG8_LAS bf16x8*)(lds + PG8_SB(b, h) + boff + n * 2048 + k * 1024); } while (0)
; #define PG8_MMA(ai, bj, At, Bt) do { __builtin_amdgcn_s_setprio(1); _Pragma("unroll") for (int m = 0; m < 4; ++m) _Pragma("unroll") for (int n = 0; n < 2; ++n) _Pragma("unroll") for (int k = 0; k < 2; ++k) \
;         acc[ai][bj][m][n] = __builtin_amdgcn_mfma_f32_16x16x32_bf16(Bt[n][k], At[m][k], acc[ai][bj][m][n], 0, 0, 0); __builtin_amdgcn_s_setprio(0); } while (0)
; #define PG8_WAIT_V(n) asm volatile("s_waitcnt vmcnt(" #n ")" ::: "memory")
; #define PG8_WAIT_L(n) asm volatile("s_waitcnt lgkmcnt(" #n ")" ::: "memory")
; #define PG8_BAR __builtin_amdgcn_s_barrier()
; #define PG8_SCHED __builtin_amdgcn_sched_barrier(0)
; template <class Epi, class Sched>
; __device__ __forceinline__ void gemm_phase(PG8_LAS unsigned char* lds, const Gemm g, const Sched& S, const Epi& E) {
;     ...
;             PG8_WAIT_L(8); PG8_BAR; PG8_WAIT_L(0); PG8_MMA(0, 0, At, B0); PG8_BAR; PG8_SCHED;
;             PG8_LDB(B1, 1, 1); PG8_STAGE(PG8_SB(1, 0), b3, voffB);
;             PG8_BAR; PG8_WAIT_L(0); PG8_MMA(0, 1, At, B1); PG8_BAR;
;             PG8_LDA(At, 1, 1); PG8_STAGE(PG8_SA(1, 0), a3, voffA);
;             PG8_BAR; PG8_WAIT_L(0); PG8_MMA(1, 0, At, B0); PG8_BAR; PG8_SCHED;
;             PG8_STAGE(PG8_SB(1, 1), b3 + hstepB, voffB);
;             PG8_WAIT_V(6); PG8_BAR; PG8_MMA(1, 1, At, B1); PG8_BAR;
;     DI void operator()(const f32x4 (&acc)[2][2][4][2], const Unit& u, int wr, int wc, int fr, int fq) const {
;         const int row0 = u.pm * 256 + wr * 64 + fr, c0 = u.pn * 128 + wc * 32 + 8 * fq;
	s_waitcnt lgkmcnt(0)
	s_setprio 1
	s_waitcnt lgkmcnt(0)
	v_mfma_f32_16x16x32_bf16 v[34:37], v[194:197], v[10:13], v[50:53]
	v_mfma_f32_16x16x32_bf16 v[134:137], v[198:201], v[46:49], v[34:37]
	v_mfma_f32_16x16x32_bf16 v[34:37], v[206:209], v[10:13], v[54:57]
	v_mfma_f32_16x16x32_bf16 v[58:61], v[210:213], v[46:49], v[34:37]
	v_mfma_f32_16x16x32_bf16 v[34:37], v[194:197], v[86:89], v[202:205]
	v_mfma_f32_16x16x32_bf16 v[126:129], v[198:201], v[94:97], v[34:37]
	v_mfma_f32_16x16x32_bf16 v[34:37], v[206:209], v[86:89], v[62:65]
	v_mfma_f32_16x16x32_bf16 v[50:53], v[210:213], v[94:97], v[34:37]
	v_mfma_f32_16x16x32_bf16 v[34:37], v[194:197], v[102:105], v[66:69]
	v_mfma_f32_16x16x32_bf16 v[118:121], v[198:201], v[114:117], v[34:37]
	v_mfma_f32_16x16x32_bf16 v[34:37], v[206:209], v[102:105], v[70:73]
	v_mfma_f32_16x16x32_bf16 v[42:45], v[210:213], v[114:117], v[34:37]
	v_mfma_f32_16x16x32_bf16 v[34:37], v[194:197], v[214:217], v[74:77]
	v_mfma_f32_16x16x32_bf16 v[110:113], v[198:201], v[238:241], v[34:37]
	v_mfma_f32_16x16x32_bf16 v[34:37], v[206:209], v[214:217], v[78:81]
	v_mfma_f32_16x16x32_bf16 v[34:37], v[210:213], v[238:241], v[34:37]
	s_setprio 0
	s_barrier
	s_mov_b32 m0, s72
	v_lshl_add_u64 v[54:55], v[242:243], 0, s[22:23]
	ds_read_b128 v[70:73], v246
	ds_read_b128 v[74:77], v246 offset:1024
	ds_read_b128 v[78:81], v246 offset:2048
	ds_read_b128 v[202:205], v246 offset:3072
	global_load_lds_dwordx4 v[54:55], off
	v_lshl_add_u64 v[54:55], v[244:245], 0, s[22:23]
	s_mov_b32 m0, s70
	s_nop 0
	global_load_lds_dwordx4 v[54:55], off
	s_barrier
	s_waitcnt lgkmcnt(0)
	s_setprio 1
	s_waitcnt lgkmcnt(0)
	v_mfma_f32_16x16x32_bf16 v[54:57], v[70:73], v[10:13], v[98:101]
	v_mfma_f32_16x16x32_bf16 v[10:13], v[78:81], v[10:13], v[18:21]
	v_mfma_f32_16x16x32_bf16 v[62:65], v[202:205], v[46:49], v[10:13]
	v_mfma_f32_16x16x32_bf16 v[10:13], v[70:73], v[86:89], v[22:25]
	v_mfma_f32_16x16x32_bf16 v[130:133], v[74:77], v[94:97], v[10:13]
	v_mfma_f32_16x16x32_bf16 v[10:13], v[78:81], v[86:89], v[26:29]
	v_mfma_f32_16x16x32_bf16 v[138:141], v[74:77], v[46:49], v[54:57]
	v_mfma_f32_16x16x32_bf16 v[54:57], v[202:205], v[94:97], v[10:13]
	v_mfma_f32_16x16x32_bf16 v[10:13], v[70:73], v[102:105], v[30:33]
	v_mfma_f32_16x16x32_bf16 v[122:125], v[74:77], v[114:117], v[10:13]
	v_mfma_f32_16x16x32_bf16 v[10:13], v[78:81], v[102:105], v[172:175]
	v_mfma_f32_16x16x32_bf16 v[46:49], v[202:205], v[114:117], v[10:13]
	v_mfma_f32_16x16x32_bf16 v[10:13], v[70:73], v[214:217], v[38:41]
	v_mfma_f32_16x16x32_bf16 v[114:117], v[74:77], v[238:241], v[10:13]
	v_mfma_f32_16x16x32_bf16 v[10:13], v[78:81], v[214:217], v[176:179]
	v_mfma_f32_16x16x32_bf16 v[38:41], v[202:205], v[238:241], v[10:13]
	s_setprio 0
	s_mov_b32 m0, s53
	s_nop 4
	v_lshl_add_u64 v[10:11], v[250:251], 0, s[22:23]
	s_barrier
	ds_read_b128 v[22:25], v192 offset:49152
	ds_read_b128 v[30:33], v192 offset:50176
	ds_read_b128 v[172:175], v192 offset:51200
	ds_read_b128 v[176:179], v192 offset:52224
	ds_read_b128 v[214:217], v192 offset:53248
	ds_read_b128 v[238:241], v192 offset:54272
	ds_read_b128 v[242:245], v192 offset:55296
	ds_read_b128 v[246:249], v192 offset:56320
	global_load_lds_dwordx4 v[10:11], off
	v_lshl_add_u64 v[10:11], v[252:253], 0, s[22:23]
	s_mov_b32 m0, s54
	s_nop 0
	global_load_lds_dwordx4 v[10:11], off
	s_barrier
	s_waitcnt lgkmcnt(0)
	s_setprio 1
	s_waitcnt lgkmcnt(0)
	v_mfma_f32_16x16x32_bf16 v[10:13], v[194:197], v[22:25], v[218:221]
	v_mfma_f32_16x16x32_bf16 v[102:105], v[198:201], v[30:33], v[10:13]
	v_mfma_f32_16x16x32_bf16 v[10:13], v[206:209], v[22:25], v[222:225]
	v_mfma_f32_16x16x32_bf16 v[26:29], v[210:213], v[30:33], v[10:13]
	v_mfma_f32_16x16x32_bf16 v[10:13], v[194:197], v[172:175], v[226:229]
	v_mfma_f32_16x16x32_bf16 v[94:97], v[198:201], v[176:179], v[10:13]
	v_mfma_f32_16x16x32_bf16 v[10:13], v[206:209], v[172:175], v[160:163]
	v_mfma_f32_16x16x32_bf16 v[18:21], v[210:213], v[176:179], v[10:13]
	v_mfma_f32_16x16x32_bf16 v[10:13], v[194:197], v[214:217], v[164:167]
	v_mfma_f32_16x16x32_bf16 v[2:5], v[194:197], v[242:245], v[2:5]
	v_mfma_f32_16x16x32_bf16 v[86:89], v[198:201], v[238:241], v[10:13]
	v_mfma_f32_16x16x32_bf16 v[10:13], v[206:209], v[214:217], v[168:171]
	v_mfma_f32_16x16x32_bf16 v[66:69], v[198:201], v[246:249], v[2:5]
	v_mfma_f32_16x16x32_bf16 v[2:5], v[206:209], v[242:245], v[6:9]
	v_mfma_f32_16x16x32_bf16 v[10:13], v[210:213], v[238:241], v[10:13]
	v_mfma_f32_16x16x32_bf16 v[2:5], v[210:213], v[246:249], v[2:5]
	s_setprio 0
	s_barrier
	s_add_u32 s8, s8, 0x10080
	s_addc_u32 s9, s9, 0
	s_mov_b32 m0, s41
	v_lshl_add_u64 v[6:7], s[8:9], 0, v[144:145]
	global_load_lds_dwordx4 v[6:7], off
	v_lshl_add_u64 v[6:7], s[8:9], 0, v[148:149]
	s_mov_b32 m0, s40
	s_nop 0
	global_load_lds_dwordx4 v[6:7], off
	s_waitcnt vmcnt(6)
	s_barrier
	s_setprio 1
	v_mfma_f32_16x16x32_bf16 v[6:9], v[70:73], v[22:25], v[106:109]
	v_mfma_f32_16x16x32_bf16 v[106:109], v[74:77], v[30:33], v[6:9]
	v_mfma_f32_16x16x32_bf16 v[6:9], v[78:81], v[22:25], v[14:17]
	v_mfma_f32_16x16x32_bf16 v[30:33], v[202:205], v[30:33], v[6:9]
	v_mfma_f32_16x16x32_bf16 v[6:9], v[70:73], v[172:175], v[230:233]
	v_mfma_f32_16x16x32_bf16 v[98:101], v[74:77], v[176:179], v[6:9]
	v_mfma_f32_16x16x32_bf16 v[6:9], v[78:81], v[172:175], v[90:93]
	v_mfma_f32_16x16x32_bf16 v[22:25], v[202:205], v[176:179], v[6:9]
	v_mfma_f32_16x16x32_bf16 v[6:9], v[70:73], v[214:217], v[234:237]
	v_mfma_f32_16x16x32_bf16 v[90:93], v[74:77], v[238:241], v[6:9]
	v_mfma_f32_16x16x32_bf16 v[6:9], v[78:81], v[214:217], v[180:183]
	v_mfma_f32_16x16x32_bf16 v[14:17], v[202:205], v[238:241], v[6:9]
	v_mfma_f32_16x16x32_bf16 v[6:9], v[70:73], v[242:245], v[82:85]
	v_mfma_f32_16x16x32_bf16 v[70:73], v[74:77], v[246:249], v[6:9]
	v_mfma_f32_16x16x32_bf16 v[6:9], v[78:81], v[242:245], v[184:187]
	v_mfma_f32_16x16x32_bf16 v[6:9], v[202:205], v[246:249], v[6:9]
	s_setprio 0
	v_lshl_or_b32 v162, s65, 7, v190
	v_ashrrev_i32_e32 v163, 31, v162
	v_lshlrev_b64 v[78:79], 2, v[162:163]
	v_lshl_add_u64 v[164:165], s[14:15], 0, v[78:79]
	s_barrier
; __device__ __forceinline__ unsigned cvt_pk_bf16(float lo, float hi) { unsigned r; asm volatile("v_cvt_pk_bf16_f32 %0, %1, %2" : "=v"(r) : "v"(lo), "v"(hi)); return r; }
; DI float lo_f(unsigned w) { return __uint_as_float(w << 16); }
; DI float hi_f(unsigned w) { return __uint_as_float(w & 0xffff0000u); }
; DI float sigmoid_(float x) { return rcp_(1.f + __expf(-x)); }
;     DI void operator()(const f32x4 (&acc)[2][2][4][2], const Unit& u, int wr, int wc, int fr, int fq) const {
;         const int row0 = u.pm * 256 + wr * 64 + fr, c0 = u.pn * 128 + wc * 32 + 8 * fq;
; #pragma unroll
;         for (int n = 0; n < 2; ++n) {
;             const int c4 = c0 + 4 * n;
;             float k4[4], ba4[4], bx4[4];
; #pragma unroll
;             for (int j = 0; j < 4; ++j) { k4[j] = lam[c4 + j]; ba4[j] = ba[c4 + j]; bx4[j] = bx[c4 + j]; }
;             u32x2 xws[8];
; #pragma unroll
;             for (int q = 0; q < 8; ++q) xws[q] = *(const u32x2*)(XC + (size_t)(row0 + (q >> 2) * 128 + (q & 3) * 16) * LRU + c4);
; #pragma unroll
;             for (int ai = 0; ai < 2; ++ai)
; #pragma unroll
;                 for (int m = 0; m < 4; ++m) { const int row = row0 + ai * 128 + m * 16; const bool first = (row & (SEQ_ - 1)) == 0;
;                     const u32x2 xw = xws[ai * 4 + m];
;                     const float xv[4] = {lo_f(xw.x), hi_f(xw.x), lo_f(xw.y), hi_f(xw.y)};
;                     float la[4], uu[4];
; #pragma unroll
;                     for (int j = 0; j < 4; ++j) { const float r = sigmoid_(acc[ai][0][m][n][j] + ba4[j]), ig = sigmoid_(acc[ai][1][m][n][j] + bx4[j]);
;                         la[j] = k4[j] * r; const float om = 1.f - __expf(2.f * la[j]); const float mult = first ? 1.f : __builtin_amdgcn_sqrtf(fmaxf(om, 0.f)); uu[j] = xv[j] * ig * mult; }
;                     u32x2 w1, w2;
;                     w1.x = pg8::cvt_pk_bf16(la[0], la[1]); w1.y = pg8::cvt_pk_bf16(la[2], la[3]);
;                     w2.x = pg8::cvt_pk_bf16(uu[0], uu[1]); w2.y = pg8::cvt_pk_bf16(uu[2], uu[3]);
;                     *(u32x2*)(LA + (size_t)row * ldla + c4) = w1; *(u32x2*)(U + (size_t)row * LRU + c4) = w2; }
	global_load_dwordx4 v[82:85], v[164:165], off
	v_lshl_add_u64 v[160:161], s[16:17], 0, v[78:79]
	global_load_dwordx4 v[74:77], v[160:161], off
	v_lshlrev_b64 v[166:167], 1, v[162:163]
	v_lshl_add_u32 v194, s64, 8, v188
	v_lshl_add_u64 v[168:169], s[12:13], 0, v[166:167]
	v_mad_i64_i32 v[80:81], s[8:9], v194, s51, v[168:169]
	v_lshl_add_u64 v[78:79], s[18:19], 0, v[78:79]
	global_load_dwordx2 v[202:203], v[80:81], off
	v_or_b32_e32 v163, 16, v194
	global_load_dwordx4 v[78:81], v[78:79], off
	v_or_b32_e32 v195, 32, v194
	v_or_b32_e32 v196, 48, v194
	v_add_u32_e32 v197, 0x80, v194
	v_add_u32_e32 v198, 0x90, v194
	v_add_u32_e32 v199, 0xa0, v194
	v_add_u32_e32 v200, 0xb0, v194
	v_mad_i64_i32 v[170:171], s[8:9], v163, s51, v[168:169]
	v_mad_i64_i32 v[172:173], s[8:9], v195, s51, v[168:169]
	v_mad_i64_i32 v[176:177], s[8:9], v196, s51, v[168:169]
	v_mad_i64_i32 v[206:207], s[8:9], v197, s51, v[168:169]
	v_mad_i64_i32 v[208:209], s[8:9], v198, s51, v[168:169]
	v_mad_i64_i32 v[210:211], s[8:9], v199, s51, v[168:169]
	v_mad_i64_i32 v[168:169], s[8:9], v200, s51, v[168:169]
	global_load_dwordx2 v[212:213], v[170:171], off
	global_load_dwordx2 v[184:185], v[172:173], off
	global_load_dwordx2 v[180:181], v[176:177], off
	s_nop 0
	global_load_dwordx2 v[176:177], v[206:207], off
	global_load_dwordx2 v[172:173], v[208:209], off
	global_load_dwordx2 v[170:171], v[210:211], off
	s_nop 0
	global_load_dwordx2 v[168:169], v[168:169], off
	v_mad_i64_i32 v[204:205], s[8:9], v194, s51, 0
	v_and_b32_e32 v201, 0x7cf, v194
	v_mad_i64_i32 v[186:187], s[8:9], v163, s51, 0
	v_mad_i64_i32 v[182:183], s[8:9], v195, s51, 0
	v_mad_i64_i32 v[178:179], s[8:9], v196, s51, 0
	v_mad_i64_i32 v[174:175], s[8:9], v197, s51, 0
	v_cmp_eq_u32_e64 s[8:9], 0, v201
	s_add_i32 s56, s56, s74
	s_mov_b32 s65, s30
	s_mov_b32 s64, s3
	s_mov_b64 s[40:41], s[36:37]
	s_waitcnt vmcnt(0)
	v_add_f32_e32 v134, v134, v82
	v_add_f32_e32 v135, v135, v83
	v_mul_f32_e32 v134, 0xbfb8aa3b, v134
	v_mul_f32_e32 v135, 0xbfb8aa3b, v135
	v_exp_f32_e32 v134, v134
	v_exp_f32_e32 v135, v135
	v_add_f32_e32 v139, v139, v75
	v_add_f32_e32 v138, v138, v74
	v_add_f32_e32 v134, 1.0, v134
	v_add_f32_e32 v135, 1.0, v135
	v_rcp_f32_e32 v134, v134
	v_mul_f32_e32 v139, 0xbfb8aa3b, v139
	v_rcp_f32_e32 v135, v135
	v_mul_f32_e32 v138, 0xbfb8aa3b, v138
	v_exp_f32_e32 v139, v139
	v_exp_f32_e32 v138, v138
	v_mul_f32_e32 v134, v78, v134
	v_mul_f32_e32 v135, v79, v135
	v_add_f32_e32 v208, v134, v134
	v_add_f32_e32 v136, v136, v84
	v_add_f32_e32 v139, 1.0, v139
	v_add_f32_e32 v209, v135, v135
	v_mul_f32_e32 v208, 0x3fb8aa3b, v208
	v_mul_f32_e32 v136, 0xbfb8aa3b, v136
	v_add_f32_e32 v138, 1.0, v138
	v_rcp_f32_e32 v139, v139
	v_mul_f32_e32 v209, 0x3fb8aa3b, v209
	v_exp_f32_e32 v208, v208
	v_add_f32_e32 v137, v137, v85
	v_exp_f32_e32 v136, v136
	v_rcp_f32_e32 v138, v138
	v_exp_f32_e32 v209, v209
	v_mul_f32_e32 v137, 0xbfb8aa3b, v137
	v_exp_f32_e32 v137, v137
	v_lshlrev_b32_e32 v206, 16, v202
	v_and_b32_e32 v202, 0xffff0000, v202
	v_mul_f32_e32 v139, v139, v202
	v_sub_f32_e32 v202, 1.0, v208
	v_add_f32_e32 v136, 1.0, v136
	v_mul_f32_e32 v138, v138, v206
	v_sub_f32_e32 v206, 1.0, v209
	v_max_f32_e32 v202, 0, v202
	v_rcp_f32_e32 v136, v136
	v_max_f32_e32 v206, 0, v206
	v_sqrt_f32_e32 v202, v202
	v_add_f32_e32 v137, 1.0, v137
	v_sqrt_f32_e32 v206, v206
	v_rcp_f32_e32 v137, v137
	v_mul_f32_e32 v208, v80, v136
	v_cndmask_b32_e64 v136, v202, 1.0, s[8:9]
	v_cndmask_b32_e64 v201, v206, 1.0, s[8:9]
	v_mul_f32_e32 v138, v136, v138
	v_add_f32_e32 v136, v208, v208
	v_mul_f32_e32 v137, v81, v137
	v_add_f32_e32 v140, v140, v76
	v_mul_f32_e32 v139, v139, v201
	v_mul_f32_e32 v136, 0x3fb8aa3b, v136
	v_add_f32_e32 v201, v137, v137
	v_mul_f32_e32 v140, 0xbfb8aa3b, v140
	v_exp_f32_e32 v136, v136
	v_add_f32_e32 v141, v141, v77
	v_mul_f32_e32 v201, 0x3fb8aa3b, v201
	v_exp_f32_e32 v140, v140
	v_mul_f32_e32 v141, 0xbfb8aa3b, v141
	v_exp_f32_e32 v201, v201
	v_exp_f32_e32 v141, v141
	v_sub_f32_e32 v136, 1.0, v136
	v_add_f32_e32 v140, 1.0, v140
	v_max_f32_e32 v136, 0, v136
	v_sub_f32_e32 v201, 1.0, v201
	v_add_f32_e32 v127, v127, v83
	v_sqrt_f32_e32 v136, v136
	v_rcp_f32_e32 v140, v140
	v_add_f32_e32 v141, 1.0, v141
	v_max_f32_e32 v201, 0, v201
	v_add_f32_e32 v130, v130, v74
	v_mul_f32_e32 v127, 0xbfb8aa3b, v127
	v_sqrt_f32_e32 v201, v201
	v_rcp_f32_e32 v141, v141
	v_mul_f32_e32 v130, 0xbfb8aa3b, v130
	v_exp_f32_e32 v127, v127
	v_exp_f32_e32 v130, v130
	v_lshlrev_b32_e32 v207, 16, v203
	v_and_b32_e32 v203, 0xffff0000, v203
	v_cndmask_b32_e64 v136, v136, 1.0, s[8:9]
	v_mul_f32_e32 v140, v140, v207
	v_mul_f32_e32 v140, v140, v136
	v_cndmask_b32_e64 v136, v201, 1.0, s[8:9]
	v_mul_f32_e32 v141, v141, v203
	v_add_f32_e32 v127, 1.0, v127
	v_mul_f32_e32 v141, v141, v136
	v_cvt_pk_bf16_f32 v136, v134, v135
	v_lshl_add_u64 v[134:135], v[204:205], 1, s[20:21]
	v_add_f32_e32 v130, 1.0, v130
	v_rcp_f32_e32 v127, v127
	v_cvt_pk_bf16_f32 v137, v208, v137
	v_lshl_add_u64 v[134:135], v[134:135], 0, v[166:167]
	v_rcp_f32_e32 v130, v130
	v_cvt_pk_bf16_f32 v138, v138, v139
	v_cvt_pk_bf16_f32 v139, v140, v141
	v_mov_b32_e32 v214, v136
	v_mov_b32_e32 v215, v137
	v_mad_i64_i32 v[136:137], s[38:39], v194, s51, v[156:157]
	v_lshl_add_u64 v[136:137], v[136:137], 0, v[166:167]
	v_mov_b32_e32 v216, v138
	v_mov_b32_e32 v217, v139
	v_lshlrev_b32_e32 v138, 16, v212
	v_mul_f32_e32 v127, v79, v127
	v_mul_f32_e32 v130, v130, v138
	v_add_f32_e32 v131, v131, v75
	v_add_f32_e32 v138, v127, v127
	v_mul_f32_e32 v131, 0xbfb8aa3b, v131
	v_mul_f32_e32 v138, 0x3fb8aa3b, v138
	v_add_f32_e32 v128, v128, v84
	v_exp_f32_e32 v131, v131
	v_exp_f32_e32 v138, v138
	v_mul_f32_e32 v128, 0xbfb8aa3b, v128
; __device__ __forceinline__ unsigned cvt_pk_bf16(float lo, float hi) { unsigned r; asm volatile("v_cvt_pk_bf16_f32 %0, %1, %2" : "=v"(r) : "v"(lo), "v"(hi)); return r; }
; DI float lo_f(unsigned w) { return __uint_as_float(w << 16); }
; DI float hi_f(unsigned w) { return __uint_as_float(w & 0xffff0000u); }
; DI float sigmoid_(float x) { return rcp_(1.f + __expf(-x)); }
;     DI void operator()(const f32x4 (&acc)[2][2][4][2], const Unit& u, int wr, int wc, int fr, int fq) const {
;     ...
;             for (int ai = 0; ai < 2; ++ai)
; #pragma unroll
;                 for (int m = 0; m < 4; ++m) { const int row = row0 + ai * 128 + m * 16; const bool first = (row & (SEQ_ - 1)) == 0;
;                     const u32x2 xw = xws[ai * 4 + m];
;                     const float xv[4] = {lo_f(xw.x), hi_f(xw.x), lo_f(xw.y), hi_f(xw.y)};
;                     float la[4], uu[4];
; #pragma unroll
;                     for (int j = 0; j < 4; ++j) { const float r = sigmoid_(acc[ai][0][m][n][j] + ba4[j]), ig = sigmoid_(acc[ai][1][m][n][j] + bx4[j]);
;                         la[j] = k4[j] * r; const float om = 1.f - __expf(2.f * la[j]); const float mult = first ? 1.f : __builtin_amdgcn_sqrtf(fmaxf(om, 0.f)); uu[j] = xv[j] * ig * mult; }
;                     u32x2 w1, w2;
;                     w1.x = pg8::cvt_pk_bf16(la[0], la[1]); w1.y = pg8::cvt_pk_bf16(la[2], la[3]);
;                     w2.x = pg8::cvt_pk_bf16(uu[0], uu[1]); w2.y = pg8::cvt_pk_bf16(uu[2], uu[3]);
;                     *(u32x2*)(LA + (size_t)row * ldla + c4) = w1; *(u32x2*)(U + (size_t)row * LRU + c4) = w2; }
	v_add_f32_e32 v129, v129, v85
	v_add_f32_e32 v126, v126, v82
	v_exp_f32_e32 v128, v128
	v_mul_f32_e32 v129, 0xbfb8aa3b, v129
	v_mul_f32_e32 v126, 0xbfb8aa3b, v126
	v_exp_f32_e32 v129, v129
	v_exp_f32_e32 v126, v126
	v_add_f32_e32 v131, 1.0, v131
	v_sub_f32_e32 v138, 1.0, v138
	v_rcp_f32_e32 v131, v131
	v_max_f32_e32 v138, 0, v138
	v_add_f32_e32 v128, 1.0, v128
	v_sqrt_f32_e32 v138, v138
	v_rcp_f32_e32 v128, v128
	v_add_f32_e32 v129, 1.0, v129
	v_add_f32_e32 v126, 1.0, v126
	v_rcp_f32_e32 v129, v129
	v_and_b32_e32 v139, 0xffff0000, v212
	v_rcp_f32_e32 v126, v126
	v_mul_f32_e32 v131, v131, v139
	v_mul_f32_e32 v131, v138, v131
	v_mul_f32_e32 v138, v80, v128
	v_add_f32_e32 v132, v132, v76
	v_add_f32_e32 v128, v138, v138
	v_mul_f32_e32 v129, v81, v129
	v_mul_f32_e32 v126, v78, v126
	v_mul_f32_e32 v132, 0xbfb8aa3b, v132
	v_mul_f32_e32 v128, 0x3fb8aa3b, v128
	v_add_f32_e32 v133, v133, v77
	v_add_f32_e32 v139, v129, v129
	v_add_f32_e32 v141, v126, v126
	v_exp_f32_e32 v132, v132
	v_exp_f32_e32 v128, v128
	v_mul_f32_e32 v133, 0xbfb8aa3b, v133
	v_mul_f32_e32 v139, 0x3fb8aa3b, v139
	v_mul_f32_e32 v141, 0x3fb8aa3b, v141
	v_exp_f32_e32 v133, v133
	v_exp_f32_e32 v139, v139
	v_exp_f32_e32 v141, v141
	v_add_f32_e32 v132, 1.0, v132
	v_sub_f32_e32 v128, 1.0, v128
	v_add_f32_e32 v119, v119, v83
	v_rcp_f32_e32 v132, v132
	v_max_f32_e32 v128, 0, v128
	v_add_f32_e32 v133, 1.0, v133
	v_sub_f32_e32 v139, 1.0, v139
	v_add_f32_e32 v122, v122, v74
	v_mul_f32_e32 v119, 0xbfb8aa3b, v119
	v_sub_f32_e32 v141, 1.0, v141
	v_sqrt_f32_e32 v128, v128
	v_rcp_f32_e32 v133, v133
	v_max_f32_e32 v139, 0, v139
	v_mul_f32_e32 v122, 0xbfb8aa3b, v122
	v_exp_f32_e32 v119, v119
	v_max_f32_e32 v141, 0, v141
	v_sqrt_f32_e32 v139, v139
	v_exp_f32_e32 v122, v122
	v_lshlrev_b32_e32 v140, 16, v213
	v_sqrt_f32_e32 v141, v141
	v_and_b32_e32 v201, 0xffff0000, v213
	v_mul_f32_e32 v132, v132, v140
	v_mul_f32_e32 v132, v132, v128
	v_mul_f32_e32 v128, v133, v201
	v_add_f32_e32 v119, 1.0, v119
	v_mul_f32_e32 v133, v128, v139
	v_cvt_pk_bf16_f32 v128, v126, v127
	v_lshl_add_u64 v[126:127], v[186:187], 1, s[20:21]
	v_add_f32_e32 v122, 1.0, v122
	v_rcp_f32_e32 v119, v119
	v_mul_f32_e32 v130, v141, v130
	v_cvt_pk_bf16_f32 v129, v138, v129
	v_lshl_add_u64 v[126:127], v[126:127], 0, v[166:167]
	v_rcp_f32_e32 v122, v122
	v_cvt_pk_bf16_f32 v130, v130, v131
	v_cvt_pk_bf16_f32 v131, v132, v133
	v_mov_b32_e32 v218, v128
	v_mov_b32_e32 v219, v129
	v_mad_i64_i32 v[128:129], s[38:39], v163, s51, v[156:157]
	v_lshl_add_u64 v[128:129], v[128:129], 0, v[166:167]
	v_mov_b32_e32 v220, v130
	v_mov_b32_e32 v221, v131
	v_lshlrev_b32_e32 v130, 16, v184
	v_mul_f32_e32 v119, v79, v119
	v_mul_f32_e32 v122, v122, v130
	v_add_f32_e32 v123, v123, v75
	v_add_f32_e32 v130, v119, v119
	v_mul_f32_e32 v123, 0xbfb8aa3b, v123
	v_mul_f32_e32 v130, 0x3fb8aa3b, v130
	v_add_f32_e32 v120, v120, v84
	v_exp_f32_e32 v123, v123
	v_exp_f32_e32 v130, v130
	v_mul_f32_e32 v120, 0xbfb8aa3b, v120
	v_add_f32_e32 v121, v121, v85
	v_add_f32_e32 v118, v118, v82
	v_exp_f32_e32 v120, v120
	v_mul_f32_e32 v121, 0xbfb8aa3b, v121
	v_mul_f32_e32 v118, 0xbfb8aa3b, v118
	v_exp_f32_e32 v121, v121
	v_exp_f32_e32 v118, v118
	v_add_f32_e32 v123, 1.0, v123
	v_sub_f32_e32 v130, 1.0, v130
	v_rcp_f32_e32 v123, v123
	v_max_f32_e32 v130, 0, v130
	v_add_f32_e32 v120, 1.0, v120
	v_sqrt_f32_e32 v130, v130
	v_rcp_f32_e32 v120, v120
	v_add_f32_e32 v121, 1.0, v121
	v_add_f32_e32 v118, 1.0, v118
	v_rcp_f32_e32 v121, v121
	v_and_b32_e32 v131, 0xffff0000, v184
	v_rcp_f32_e32 v118, v118
	v_mul_f32_e32 v123, v123, v131
	v_mul_f32_e32 v123, v130, v123
	v_mul_f32_e32 v130, v80, v120
	v_add_f32_e32 v124, v124, v76
	v_add_f32_e32 v120, v130, v130
	v_mul_f32_e32 v121, v81, v121
	v_mul_f32_e32 v118, v78, v118
	v_mul_f32_e32 v124, 0xbfb8aa3b, v124
	v_mul_f32_e32 v120, 0x3fb8aa3b, v120
	v_add_f32_e32 v125, v125, v77
	v_add_f32_e32 v131, v121, v121
	v_add_f32_e32 v133, v118, v118
	v_exp_f32_e32 v124, v124
	v_exp_f32_e32 v120, v120
	v_mul_f32_e32 v125, 0xbfb8aa3b, v125
	v_mul_f32_e32 v131, 0x3fb8aa3b, v131
	v_mul_f32_e32 v133, 0x3fb8aa3b, v133
	v_exp_f32_e32 v125, v125
	v_exp_f32_e32 v131, v131
	v_exp_f32_e32 v133, v133
	v_add_f32_e32 v124, 1.0, v124
	v_sub_f32_e32 v120, 1.0, v120
	v_add_f32_e32 v111, v111, v83
	v_rcp_f32_e32 v124, v124
	v_max_f32_e32 v120, 0, v120
	v_add_f32_e32 v125, 1.0, v125
	v_sub_f32_e32 v131, 1.0, v131
	v_add_f32_e32 v114, v114, v74
	v_mul_f32_e32 v111, 0xbfb8aa3b, v111
	v_sub_f32_e32 v133, 1.0, v133
	v_sqrt_f32_e32 v120, v120
	v_rcp_f32_e32 v125, v125
	v_max_f32_e32 v131, 0, v131
	v_mul_f32_e32 v114, 0xbfb8aa3b, v114
	v_exp_f32_e32 v111, v111
	v_max_f32_e32 v133, 0, v133
	v_sqrt_f32_e32 v131, v131
	v_exp_f32_e32 v114, v114
	v_lshlrev_b32_e32 v132, 16, v185
	v_sqrt_f32_e32 v133, v133
	v_add_f32_e32 v113, v113, v85
	v_and_b32_e32 v138, 0xffff0000, v185
	v_mul_f32_e32 v124, v124, v132
	v_add_f32_e32 v115, v115, v75
	v_mul_f32_e32 v113, 0xbfb8aa3b, v113
	v_mul_f32_e32 v124, v124, v120
	v_mul_f32_e32 v120, v125, v138
	v_mul_f32_e32 v115, 0xbfb8aa3b, v115
	v_add_f32_e32 v111, 1.0, v111
	v_exp_f32_e32 v113, v113
	v_mul_f32_e32 v125, v120, v131
	v_cvt_pk_bf16_f32 v120, v118, v119
	v_lshl_add_u64 v[118:119], v[182:183], 1, s[20:21]
	v_add_f32_e32 v114, 1.0, v114
	v_exp_f32_e32 v115, v115
	v_rcp_f32_e32 v111, v111
	v_mul_f32_e32 v122, v133, v122
	v_cvt_pk_bf16_f32 v121, v130, v121
	v_lshl_add_u64 v[118:119], v[118:119], 0, v[166:167]
	v_rcp_f32_e32 v114, v114
	v_cvt_pk_bf16_f32 v122, v122, v123
	v_cvt_pk_bf16_f32 v123, v124, v125
	v_mov_b32_e32 v222, v120
	v_mov_b32_e32 v223, v121
	v_mad_i64_i32 v[120:121], s[38:39], v195, s51, v[156:157]
	v_lshl_add_u64 v[120:121], v[120:121], 0, v[166:167]
; __device__ __forceinline__ unsigned cvt_pk_bf16(float lo, float hi) { unsigned r; asm volatile("v_cvt_pk_bf16_f32 %0, %1, %2" : "=v"(r) : "v"(lo), "v"(hi)); return r; }
; DI float lo_f(unsigned w) { return __uint_as_float(w << 16); }
; DI float hi_f(unsigned w) { return __uint_as_float(w & 0xffff0000u); }
; DI float sigmoid_(float x) { return rcp_(1.f + __expf(-x)); }
;     DI void operator()(const f32x4 (&acc)[2][2][4][2], const Unit& u, int wr, int wc, int fr, int fq) const {
;     ...
;             for (int ai = 0; ai < 2; ++ai)
; #pragma unroll
;                 for (int m = 0; m < 4; ++m) { const int row = row0 + ai * 128 + m * 16; const bool first = (row & (SEQ_ - 1)) == 0;
;                     const u32x2 xw = xws[ai * 4 + m];
;                     const float xv[4] = {lo_f(xw.x), hi_f(xw.x), lo_f(xw.y), hi_f(xw.y)};
;                     float la[4], uu[4];
; #pragma unroll
;                     for (int j = 0; j < 4; ++j) { const float r = sigmoid_(acc[ai][0][m][n][j] + ba4[j]), ig = sigmoid_(acc[ai][1][m][n][j] + bx4[j]);
;                         la[j] = k4[j] * r; const float om = 1.f - __expf(2.f * la[j]); const float mult = first ? 1.f : __builtin_amdgcn_sqrtf(fmaxf(om, 0.f)); uu[j] = xv[j] * ig * mult; }
;                     u32x2 w1, w2;
;                     w1.x = pg8::cvt_pk_bf16(la[0], la[1]); w1.y = pg8::cvt_pk_bf16(la[2], la[3]);
;                     w2.x = pg8::cvt_pk_bf16(uu[0], uu[1]); w2.y = pg8::cvt_pk_bf16(uu[2], uu[3]);
;                     *(u32x2*)(LA + (size_t)row * ldla + c4) = w1; *(u32x2*)(U + (size_t)row * LRU + c4) = w2; }
	v_add_f32_e32 v113, 1.0, v113
	v_mov_b32_e32 v224, v122
	v_mov_b32_e32 v225, v123
	v_add_f32_e32 v110, v110, v82
	v_lshlrev_b32_e32 v122, 16, v180
	v_add_f32_e32 v115, 1.0, v115
	v_mul_f32_e32 v111, v79, v111
	v_rcp_f32_e32 v113, v113
	v_mul_f32_e32 v110, 0xbfb8aa3b, v110
	v_mul_f32_e32 v114, v114, v122
	v_rcp_f32_e32 v115, v115
	v_add_f32_e32 v122, v111, v111
	v_add_f32_e32 v112, v112, v84
	v_exp_f32_e32 v110, v110
	v_mul_f32_e32 v122, 0x3fb8aa3b, v122
	v_mul_f32_e32 v112, 0xbfb8aa3b, v112
	v_exp_f32_e32 v122, v122
	v_exp_f32_e32 v112, v112
	v_and_b32_e32 v123, 0xffff0000, v180
	v_mul_f32_e32 v113, v81, v113
	v_mul_f32_e32 v115, v115, v123
	v_add_f32_e32 v117, v117, v77
	v_add_f32_e32 v123, v113, v113
	v_add_f32_e32 v102, v102, v82
	v_add_f32_e32 v110, 1.0, v110
	v_mul_f32_e32 v117, 0xbfb8aa3b, v117
	v_mul_f32_e32 v123, 0x3fb8aa3b, v123
	v_mul_f32_e32 v102, 0xbfb8aa3b, v102
	v_rcp_f32_e32 v110, v110
	v_sub_f32_e32 v122, 1.0, v122
	v_add_f32_e32 v112, 1.0, v112
	v_exp_f32_e32 v117, v117
	v_exp_f32_e32 v123, v123
	v_exp_f32_e32 v102, v102
	v_max_f32_e32 v122, 0, v122
	v_rcp_f32_e32 v112, v112
	v_sqrt_f32_e32 v122, v122
	v_mul_f32_e32 v110, v78, v110
	v_add_f32_e32 v117, 1.0, v117
	v_sub_f32_e32 v123, 1.0, v123
	v_add_f32_e32 v102, 1.0, v102
	v_add_f32_e32 v125, v110, v110
	v_mul_f32_e32 v112, v80, v112
	v_rcp_f32_e32 v117, v117
	v_max_f32_e32 v123, 0, v123
	v_rcp_f32_e32 v102, v102
	v_mul_f32_e32 v125, 0x3fb8aa3b, v125
	v_add_f32_e32 v116, v116, v76
	v_mul_f32_e32 v115, v122, v115
	v_add_f32_e32 v122, v112, v112
	v_sqrt_f32_e32 v123, v123
	v_exp_f32_e32 v125, v125
	v_mul_f32_e32 v116, 0xbfb8aa3b, v116
	v_mul_f32_e32 v122, 0x3fb8aa3b, v122
	v_and_b32_e32 v130, 0xffff0000, v181
	v_exp_f32_e32 v116, v116
	v_exp_f32_e32 v122, v122
	v_mul_f32_e32 v117, v117, v130
	v_mul_f32_e32 v102, v78, v102
	v_mul_f32_e32 v117, v117, v123
	v_add_f32_e32 v123, v102, v102
	v_sub_f32_e32 v125, 1.0, v125
	v_add_f32_e32 v106, v106, v74
	v_mul_f32_e32 v123, 0x3fb8aa3b, v123
	v_add_f32_e32 v103, v103, v83
	v_max_f32_e32 v125, 0, v125
	v_add_f32_e32 v116, 1.0, v116
	v_sub_f32_e32 v122, 1.0, v122
	v_mul_f32_e32 v106, 0xbfb8aa3b, v106
	v_exp_f32_e32 v123, v123
	v_mul_f32_e32 v103, 0xbfb8aa3b, v103
	v_sqrt_f32_e32 v125, v125
	v_rcp_f32_e32 v116, v116
	v_max_f32_e32 v122, 0, v122
	v_exp_f32_e32 v106, v106
	v_exp_f32_e32 v103, v103
	v_sqrt_f32_e32 v122, v122
	v_lshlrev_b32_e32 v124, 16, v181
	v_cvt_pk_bf16_f32 v110, v110, v111
	v_cvt_pk_bf16_f32 v111, v112, v113
	v_lshl_add_u64 v[112:113], v[178:179], 1, s[20:21]
	v_sub_f32_e32 v123, 1.0, v123
	v_mul_f32_e32 v114, v125, v114
	v_mul_f32_e32 v116, v116, v124
	v_lshl_add_u64 v[112:113], v[112:113], 0, v[166:167]
	v_add_f32_e32 v106, 1.0, v106
	v_max_f32_e32 v123, 0, v123
	v_add_f32_e32 v103, 1.0, v103
	v_mul_f32_e32 v116, v116, v122
	v_cvt_pk_bf16_f32 v114, v114, v115
	v_cvt_pk_bf16_f32 v115, v116, v117
	v_mov_b32_e32 v226, v110
	v_mov_b32_e32 v227, v111
	v_mad_i64_i32 v[110:111], s[38:39], v196, s51, v[156:157]
	v_rcp_f32_e32 v106, v106
	v_sqrt_f32_e32 v123, v123
	v_rcp_f32_e32 v103, v103
	v_lshl_add_u64 v[110:111], v[110:111], 0, v[166:167]
	v_mov_b32_e32 v228, v114
	v_mov_b32_e32 v229, v115
	v_and_b32_e32 v114, 0x7cf, v197
	v_lshlrev_b32_e32 v115, 16, v176
	v_cmp_eq_u32_e32 vcc, 0, v114
	v_mul_f32_e32 v106, v106, v115
	v_mul_f32_e32 v103, v79, v103
	v_cndmask_b32_e64 v114, v123, 1.0, vcc
	v_mul_f32_e32 v106, v114, v106
	v_add_f32_e32 v114, v103, v103
	v_mul_f32_e32 v114, 0x3fb8aa3b, v114
	v_add_f32_e32 v107, v107, v75
	v_exp_f32_e32 v114, v114
	v_mul_f32_e32 v107, 0xbfb8aa3b, v107
	v_add_f32_e32 v104, v104, v84
	v_exp_f32_e32 v107, v107
	v_mul_f32_e32 v104, 0xbfb8aa3b, v104
	v_add_f32_e32 v105, v105, v85
	v_exp_f32_e32 v104, v104
	v_mul_f32_e32 v105, 0xbfb8aa3b, v105
	v_exp_f32_e32 v105, v105
	v_sub_f32_e32 v114, 1.0, v114
	v_max_f32_e32 v114, 0, v114
	v_add_f32_e32 v107, 1.0, v107
	v_sqrt_f32_e32 v114, v114
	v_rcp_f32_e32 v107, v107
	v_add_f32_e32 v104, 1.0, v104
	v_rcp_f32_e32 v104, v104
	v_add_f32_e32 v105, 1.0, v105
	v_rcp_f32_e32 v105, v105
	v_and_b32_e32 v116, 0xffff0000, v176
	v_cndmask_b32_e64 v114, v114, 1.0, vcc
	v_mul_f32_e32 v107, v107, v116
	v_mul_f32_e32 v107, v114, v107
	v_mul_f32_e32 v114, v80, v104
	v_add_f32_e32 v104, v114, v114
	v_mul_f32_e32 v105, v81, v105
	v_add_f32_e32 v108, v108, v76
	v_mul_f32_e32 v104, 0x3fb8aa3b, v104
	v_add_f32_e32 v115, v105, v105
	v_mul_f32_e32 v108, 0xbfb8aa3b, v108
	v_exp_f32_e32 v104, v104
	v_add_f32_e32 v109, v109, v77
	v_mul_f32_e32 v115, 0x3fb8aa3b, v115
	v_exp_f32_e32 v108, v108
	v_mul_f32_e32 v109, 0xbfb8aa3b, v109
	v_exp_f32_e32 v115, v115
	v_exp_f32_e32 v109, v109
	v_sub_f32_e32 v104, 1.0, v104
	v_add_f32_e32 v108, 1.0, v108
	v_max_f32_e32 v104, 0, v104
	v_sub_f32_e32 v115, 1.0, v115
	v_add_f32_e32 v95, v95, v83
	v_sqrt_f32_e32 v104, v104
	v_rcp_f32_e32 v108, v108
	v_add_f32_e32 v109, 1.0, v109
	v_max_f32_e32 v115, 0, v115
	v_add_f32_e32 v98, v98, v74
	v_mul_f32_e32 v95, 0xbfb8aa3b, v95
	v_sqrt_f32_e32 v115, v115
	v_rcp_f32_e32 v109, v109
	v_mul_f32_e32 v98, 0xbfb8aa3b, v98
	v_exp_f32_e32 v95, v95
	v_exp_f32_e32 v98, v98
	v_lshlrev_b32_e32 v117, 16, v177
	v_and_b32_e32 v122, 0xffff0000, v177
	v_cndmask_b32_e64 v104, v104, 1.0, vcc
	v_mul_f32_e32 v108, v108, v117
	v_mul_f32_e32 v108, v108, v104
	v_cndmask_b32_e64 v104, v115, 1.0, vcc
	v_mul_f32_e32 v109, v109, v122
	v_add_f32_e32 v95, 1.0, v95
	v_mul_f32_e32 v109, v109, v104
	v_cvt_pk_bf16_f32 v104, v102, v103
	v_lshl_add_u64 v[102:103], v[174:175], 1, s[20:21]
	v_add_f32_e32 v98, 1.0, v98
	v_rcp_f32_e32 v95, v95
	v_cvt_pk_bf16_f32 v105, v114, v105
	v_lshl_add_u64 v[102:103], v[102:103], 0, v[166:167]
; __device__ __forceinline__ unsigned cvt_pk_bf16(float lo, float hi) { unsigned r; asm volatile("v_cvt_pk_bf16_f32 %0, %1, %2" : "=v"(r) : "v"(lo), "v"(hi)); return r; }
; DI float lo_f(unsigned w) { return __uint_as_float(w << 16); }
; DI float hi_f(unsigned w) { return __uint_as_float(w & 0xffff0000u); }
; DI float sigmoid_(float x) { return rcp_(1.f + __expf(-x)); }
;     DI void operator()(const f32x4 (&acc)[2][2][4][2], const Unit& u, int wr, int wc, int fr, int fq) const {
;     ...
;             for (int ai = 0; ai < 2; ++ai)
; #pragma unroll
;                 for (int m = 0; m < 4; ++m) { const int row = row0 + ai * 128 + m * 16; const bool first = (row & (SEQ_ - 1)) == 0;
;                     const u32x2 xw = xws[ai * 4 + m];
;                     const float xv[4] = {lo_f(xw.x), hi_f(xw.x), lo_f(xw.y), hi_f(xw.y)};
;                     float la[4], uu[4];
; #pragma unroll
;                     for (int j = 0; j < 4; ++j) { const float r = sigmoid_(acc[ai][0][m][n][j] + ba4[j]), ig = sigmoid_(acc[ai][1][m][n][j] + bx4[j]);
;                         la[j] = k4[j] * r; const float om = 1.f - __expf(2.f * la[j]); const float mult = first ? 1.f : __builtin_amdgcn_sqrtf(fmaxf(om, 0.f)); uu[j] = xv[j] * ig * mult; }
;                     u32x2 w1, w2;
;                     w1.x = pg8::cvt_pk_bf16(la[0], la[1]); w1.y = pg8::cvt_pk_bf16(la[2], la[3]);
;                     w2.x = pg8::cvt_pk_bf16(uu[0], uu[1]); w2.y = pg8::cvt_pk_bf16(uu[2], uu[3]);
;                     *(u32x2*)(LA + (size_t)row * ldla + c4) = w1; *(u32x2*)(U + (size_t)row * LRU + c4) = w2; }
	v_rcp_f32_e32 v98, v98
	v_cvt_pk_bf16_f32 v106, v106, v107
	v_cvt_pk_bf16_f32 v107, v108, v109
	v_mov_b32_e32 v230, v104
	v_mov_b32_e32 v231, v105
	v_mad_i64_i32 v[104:105], s[38:39], v197, s51, v[156:157]
	v_lshl_add_u64 v[104:105], v[104:105], 0, v[166:167]
	v_mov_b32_e32 v232, v106
	v_mov_b32_e32 v233, v107
	v_lshlrev_b32_e32 v106, 16, v172
	v_mul_f32_e32 v95, v79, v95
	v_mul_f32_e32 v98, v98, v106
	v_add_f32_e32 v99, v99, v75
	v_add_f32_e32 v106, v95, v95
	v_mul_f32_e32 v99, 0xbfb8aa3b, v99
	v_mul_f32_e32 v106, 0x3fb8aa3b, v106
	v_add_f32_e32 v96, v96, v84
	v_exp_f32_e32 v99, v99
	v_exp_f32_e32 v106, v106
	v_mul_f32_e32 v96, 0xbfb8aa3b, v96
	v_add_f32_e32 v97, v97, v85
	v_add_f32_e32 v94, v94, v82
	v_exp_f32_e32 v96, v96
	v_mul_f32_e32 v97, 0xbfb8aa3b, v97
	v_mul_f32_e32 v94, 0xbfb8aa3b, v94
	v_exp_f32_e32 v97, v97
	v_exp_f32_e32 v94, v94
	v_add_f32_e32 v99, 1.0, v99
	v_sub_f32_e32 v106, 1.0, v106
	v_rcp_f32_e32 v99, v99
	v_max_f32_e32 v106, 0, v106
	v_add_f32_e32 v96, 1.0, v96
	v_sqrt_f32_e32 v106, v106
	v_rcp_f32_e32 v96, v96
	v_add_f32_e32 v97, 1.0, v97
	v_add_f32_e32 v94, 1.0, v94
	v_rcp_f32_e32 v97, v97
	v_and_b32_e32 v107, 0xffff0000, v172
	v_rcp_f32_e32 v94, v94
	v_mul_f32_e32 v99, v99, v107
	v_mul_f32_e32 v99, v106, v99
	v_mul_f32_e32 v106, v80, v96
	v_add_f32_e32 v100, v100, v76
	v_add_f32_e32 v96, v106, v106
	v_mul_f32_e32 v97, v81, v97
	v_mul_f32_e32 v94, v78, v94
	v_mul_f32_e32 v100, 0xbfb8aa3b, v100
	v_mul_f32_e32 v96, 0x3fb8aa3b, v96
	v_add_f32_e32 v101, v101, v77
	v_add_f32_e32 v107, v97, v97
	v_add_f32_e32 v109, v94, v94
	v_exp_f32_e32 v100, v100
	v_exp_f32_e32 v96, v96
	v_mul_f32_e32 v101, 0xbfb8aa3b, v101
	v_mul_f32_e32 v107, 0x3fb8aa3b, v107
	v_mul_f32_e32 v109, 0x3fb8aa3b, v109
	v_exp_f32_e32 v101, v101
	v_exp_f32_e32 v107, v107
	v_exp_f32_e32 v109, v109
	v_add_f32_e32 v100, 1.0, v100
	v_sub_f32_e32 v96, 1.0, v96
	v_add_f32_e32 v87, v87, v83
	v_rcp_f32_e32 v100, v100
	v_max_f32_e32 v96, 0, v96
	v_add_f32_e32 v101, 1.0, v101
	v_sub_f32_e32 v107, 1.0, v107
	v_add_f32_e32 v90, v90, v74
	v_mul_f32_e32 v87, 0xbfb8aa3b, v87
	v_sub_f32_e32 v109, 1.0, v109
	v_sqrt_f32_e32 v96, v96
	v_rcp_f32_e32 v101, v101
	v_max_f32_e32 v107, 0, v107
	v_mul_f32_e32 v90, 0xbfb8aa3b, v90
	v_exp_f32_e32 v87, v87
	v_max_f32_e32 v109, 0, v109
	v_sqrt_f32_e32 v107, v107
	v_exp_f32_e32 v90, v90
	v_lshlrev_b32_e32 v108, 16, v173
	v_sqrt_f32_e32 v109, v109
	v_and_b32_e32 v114, 0xffff0000, v173
	v_mul_f32_e32 v100, v100, v108
	v_mul_f32_e32 v100, v96, v100
	v_mul_f32_e32 v96, v101, v114
	v_add_f32_e32 v87, 1.0, v87
	v_mul_f32_e32 v101, v96, v107
	v_cvt_pk_bf16_f32 v96, v94, v95
	v_mad_i64_i32 v[94:95], s[38:39], v198, s59, v[154:155]
	v_add_f32_e32 v90, 1.0, v90
	v_rcp_f32_e32 v87, v87
	v_mul_f32_e32 v98, v109, v98
	v_cvt_pk_bf16_f32 v97, v106, v97
	v_lshl_add_u64 v[94:95], v[94:95], 0, v[166:167]
	v_rcp_f32_e32 v90, v90
	v_add_f32_e32 v66, v66, v82
	v_cvt_pk_bf16_f32 v98, v98, v99
	v_cvt_pk_bf16_f32 v99, v100, v101
	v_mov_b32_e32 v234, v96
	v_mov_b32_e32 v235, v97
	v_mad_i64_i32 v[96:97], s[38:39], v198, s51, v[156:157]
	v_mul_f32_e32 v66, 0xbfb8aa3b, v66
	v_lshl_add_u64 v[96:97], v[96:97], 0, v[166:167]
	v_exp_f32_e32 v66, v66
	v_mov_b32_e32 v236, v98
	v_mov_b32_e32 v237, v99
	v_lshlrev_b32_e32 v98, 16, v170
	v_mul_f32_e32 v87, v79, v87
	v_mul_f32_e32 v90, v90, v98
	v_add_f32_e32 v91, v91, v75
	v_add_f32_e32 v98, v87, v87
	v_mul_f32_e32 v91, 0xbfb8aa3b, v91
	v_mul_f32_e32 v98, 0x3fb8aa3b, v98
	v_add_f32_e32 v88, v88, v84
	v_exp_f32_e32 v91, v91
	v_exp_f32_e32 v98, v98
	v_mul_f32_e32 v88, 0xbfb8aa3b, v88
	v_add_f32_e32 v89, v89, v85
	v_add_f32_e32 v66, 1.0, v66
	v_add_f32_e32 v86, v86, v82
	v_exp_f32_e32 v88, v88
	v_mul_f32_e32 v89, 0xbfb8aa3b, v89
	v_rcp_f32_e32 v66, v66
	v_mul_f32_e32 v86, 0xbfb8aa3b, v86
	v_exp_f32_e32 v89, v89
	v_exp_f32_e32 v86, v86
	v_add_f32_e32 v91, 1.0, v91
	v_sub_f32_e32 v98, 1.0, v98
	v_rcp_f32_e32 v91, v91
	v_max_f32_e32 v98, 0, v98
	v_add_f32_e32 v88, 1.0, v88
	v_mul_f32_e32 v66, v78, v66
	v_sqrt_f32_e32 v98, v98
	v_rcp_f32_e32 v88, v88
	v_add_f32_e32 v89, 1.0, v89
	v_add_f32_e32 v70, v70, v74
	v_add_f32_e32 v74, v66, v66
	v_add_f32_e32 v67, v67, v83
	v_add_f32_e32 v86, 1.0, v86
	v_rcp_f32_e32 v89, v89
	v_mul_f32_e32 v70, 0xbfb8aa3b, v70
	v_mul_f32_e32 v74, 0x3fb8aa3b, v74
	v_mul_f32_e32 v67, 0xbfb8aa3b, v67
	v_and_b32_e32 v99, 0xffff0000, v170
	v_rcp_f32_e32 v86, v86
	v_exp_f32_e32 v70, v70
	v_exp_f32_e32 v74, v74
	v_exp_f32_e32 v67, v67
	v_mul_f32_e32 v91, v91, v99
	v_mul_f32_e32 v91, v98, v91
	v_mul_f32_e32 v98, v80, v88
	v_add_f32_e32 v92, v92, v76
	v_add_f32_e32 v88, v98, v98
	v_mul_f32_e32 v89, v81, v89
	v_mul_f32_e32 v86, v78, v86
	v_mul_f32_e32 v92, 0xbfb8aa3b, v92
	v_mul_f32_e32 v88, 0x3fb8aa3b, v88
	v_add_f32_e32 v93, v93, v77
	v_add_f32_e32 v99, v89, v89
	v_add_f32_e32 v70, 1.0, v70
	v_sub_f32_e32 v74, 1.0, v74
	v_add_f32_e32 v67, 1.0, v67
	v_add_f32_e32 v101, v86, v86
	v_exp_f32_e32 v92, v92
	v_exp_f32_e32 v88, v88
	v_mul_f32_e32 v93, 0xbfb8aa3b, v93
	v_mul_f32_e32 v99, 0x3fb8aa3b, v99
	v_rcp_f32_e32 v70, v70
	v_max_f32_e32 v74, 0, v74
	v_rcp_f32_e32 v67, v67
	v_mul_f32_e32 v101, 0x3fb8aa3b, v101
	v_exp_f32_e32 v93, v93
	v_exp_f32_e32 v99, v99
	v_sqrt_f32_e32 v74, v74
	v_exp_f32_e32 v101, v101
	v_lshlrev_b32_e32 v82, 16, v168
	v_add_f32_e32 v92, 1.0, v92
	v_sub_f32_e32 v88, 1.0, v88
	v_mul_f32_e32 v70, v70, v82
	v_mul_f32_e32 v67, v79, v67
	v_rcp_f32_e32 v92, v92
	v_max_f32_e32 v88, 0, v88
	v_add_f32_e32 v93, 1.0, v93
	v_sub_f32_e32 v99, 1.0, v99
	v_add_f32_e32 v71, v71, v75
	v_mul_f32_e32 v70, v74, v70
	v_add_f32_e32 v74, v67, v67
	v_add_f32_e32 v68, v68, v84
	v_add_f32_e32 v69, v69, v85
; __device__ __forceinline__ unsigned cvt_pk_bf16(float lo, float hi) { unsigned r; asm volatile("v_cvt_pk_bf16_f32 %0, %1, %2" : "=v"(r) : "v"(lo), "v"(hi)); return r; }
; DI float lo_f(unsigned w) { return __uint_as_float(w << 16); }
; DI float hi_f(unsigned w) { return __uint_as_float(w & 0xffff0000u); }
; DI float sigmoid_(float x) { return rcp_(1.f + __expf(-x)); }
;     DI void operator()(const f32x4 (&acc)[2][2][4][2], const Unit& u, int wr, int wc, int fr, int fq) const {
;     ...
;             const int c4 = c0 + 4 * n;
;             float k4[4], ba4[4], bx4[4];
; #pragma unroll
;             for (int j = 0; j < 4; ++j) { k4[j] = lam[c4 + j]; ba4[j] = ba[c4 + j]; bx4[j] = bx[c4 + j]; }
;             u32x2 xws[8];
; #pragma unroll
;             for (int q = 0; q < 8; ++q) xws[q] = *(const u32x2*)(XC + (size_t)(row0 + (q >> 2) * 128 + (q & 3) * 16) * LRU + c4);
;     ...
;             for (int ai = 0; ai < 2; ++ai)
; #pragma unroll
;                 for (int m = 0; m < 4; ++m) { const int row = row0 + ai * 128 + m * 16; const bool first = (row & (SEQ_ - 1)) == 0;
;                     const u32x2 xw = xws[ai * 4 + m];
;                     const float xv[4] = {lo_f(xw.x), hi_f(xw.x), lo_f(xw.y), hi_f(xw.y)};
;                     float la[4], uu[4];
; #pragma unroll
;                     for (int j = 0; j < 4; ++j) { const float r = sigmoid_(acc[ai][0][m][n][j] + ba4[j]), ig = sigmoid_(acc[ai][1][m][n][j] + bx4[j]);
;                         la[j] = k4[j] * r; const float om = 1.f - __expf(2.f * la[j]); const float mult = first ? 1.f : __builtin_amdgcn_sqrtf(fmaxf(om, 0.f)); uu[j] = xv[j] * ig * mult; }
;                     u32x2 w1, w2;
;                     w1.x = pg8::cvt_pk_bf16(la[0], la[1]); w1.y = pg8::cvt_pk_bf16(la[2], la[3]);
;                     w2.x = pg8::cvt_pk_bf16(uu[0], uu[1]); w2.y = pg8::cvt_pk_bf16(uu[2], uu[3]);
;                     *(u32x2*)(LA + (size_t)row * ldla + c4) = w1; *(u32x2*)(U + (size_t)row * LRU + c4) = w2; }
	v_sub_f32_e32 v101, 1.0, v101
	v_sqrt_f32_e32 v88, v88
	v_rcp_f32_e32 v93, v93
	v_max_f32_e32 v99, 0, v99
	v_mul_f32_e32 v71, 0xbfb8aa3b, v71
	v_mul_f32_e32 v74, 0x3fb8aa3b, v74
	v_mul_f32_e32 v68, 0xbfb8aa3b, v68
	v_mul_f32_e32 v69, 0xbfb8aa3b, v69
	v_max_f32_e32 v101, 0, v101
	v_sqrt_f32_e32 v99, v99
	v_exp_f32_e32 v71, v71
	v_exp_f32_e32 v74, v74
	v_exp_f32_e32 v68, v68
	v_exp_f32_e32 v69, v69
	v_lshlrev_b32_e32 v100, 16, v171
	v_sqrt_f32_e32 v101, v101
	v_and_b32_e32 v106, 0xffff0000, v171
	v_mul_f32_e32 v92, v92, v100
	v_mul_f32_e32 v92, v88, v92
	v_mul_f32_e32 v88, v93, v106
	v_mul_f32_e32 v93, v88, v99
	v_cvt_pk_bf16_f32 v88, v86, v87
	v_mad_i64_i32 v[86:87], s[38:39], v199, s59, v[154:155]
	v_add_f32_e32 v71, 1.0, v71
	v_sub_f32_e32 v74, 1.0, v74
	v_add_f32_e32 v68, 1.0, v68
	v_add_f32_e32 v69, 1.0, v69
	v_mul_f32_e32 v90, v101, v90
	v_cvt_pk_bf16_f32 v89, v98, v89
	v_lshl_add_u64 v[86:87], v[86:87], 0, v[166:167]
	v_rcp_f32_e32 v71, v71
	v_max_f32_e32 v74, 0, v74
	v_rcp_f32_e32 v68, v68
	v_rcp_f32_e32 v69, v69
	v_cvt_pk_bf16_f32 v90, v90, v91
	v_cvt_pk_bf16_f32 v91, v92, v93
	v_mov_b32_e32 v238, v88
	v_mov_b32_e32 v239, v89
	v_mad_i64_i32 v[88:89], s[38:39], v199, s51, v[156:157]
	v_sqrt_f32_e32 v74, v74
	v_lshl_add_u64 v[88:89], v[88:89], 0, v[166:167]
	v_mov_b32_e32 v240, v90
	v_mov_b32_e32 v241, v91
	v_and_b32_e32 v90, 0xffff0000, v168
	v_mul_f32_e32 v71, v71, v90
	v_mul_f32_e32 v68, v80, v68
	v_mul_f32_e32 v69, v81, v69
	v_add_f32_e32 v72, v72, v76
	v_mul_f32_e32 v71, v74, v71
	v_add_f32_e32 v74, v68, v68
	v_add_f32_e32 v73, v73, v77
	v_add_f32_e32 v75, v69, v69
	v_mul_f32_e32 v72, 0xbfb8aa3b, v72
	v_mul_f32_e32 v74, 0x3fb8aa3b, v74
	v_mul_f32_e32 v73, 0xbfb8aa3b, v73
	v_mul_f32_e32 v75, 0x3fb8aa3b, v75
	v_exp_f32_e32 v72, v72
	v_exp_f32_e32 v74, v74
	v_exp_f32_e32 v73, v73
	v_exp_f32_e32 v75, v75
	v_add_f32_e32 v72, 1.0, v72
	v_sub_f32_e32 v74, 1.0, v74
	v_add_f32_e32 v73, 1.0, v73
	v_sub_f32_e32 v75, 1.0, v75
	v_rcp_f32_e32 v72, v72
	v_max_f32_e32 v74, 0, v74
	v_rcp_f32_e32 v73, v73
	v_max_f32_e32 v75, 0, v75
	v_sqrt_f32_e32 v74, v74
	v_sqrt_f32_e32 v75, v75
	v_lshlrev_b32_e32 v91, 16, v169
	v_and_b32_e32 v78, 0xffff0000, v169
	v_cvt_pk_bf16_f32 v66, v66, v67
	v_cvt_pk_bf16_f32 v67, v68, v69
	v_cvt_pk_bf16_f32 v68, v70, v71
	v_mad_i64_i32 v[70:71], s[38:39], v200, s59, v[154:155]
	v_mul_f32_e32 v72, v72, v91
	v_mul_f32_e32 v73, v73, v78
	v_lshl_add_u64 v[78:79], v[70:71], 0, v[166:167]
	v_mul_f32_e32 v72, v74, v72
	v_mul_f32_e32 v73, v75, v73
	v_cvt_pk_bf16_f32 v69, v72, v73
	v_mov_b32_e32 v242, v66
	v_mov_b32_e32 v243, v67
	v_mad_i64_i32 v[66:67], s[38:39], v200, s51, v[156:157]
	v_lshl_add_u64 v[80:81], v[66:67], 0, v[166:167]
	v_or_b32_e32 v66, 4, v162
	v_mov_b32_e32 v244, v68
	v_mov_b32_e32 v245, v69
	v_ashrrev_i32_e32 v67, 31, v66
	v_mad_i64_i32 v[68:69], s[38:39], v194, s51, v[158:159]
	v_lshlrev_b64 v[82:83], 1, v[66:67]
	global_load_dwordx4 v[74:77], v[164:165], off offset:16
	v_lshl_add_u64 v[68:69], v[68:69], 0, v[82:83]
	global_load_dwordx2 v[106:107], v[68:69], off
	global_load_dwordx4 v[70:73], v[160:161], off offset:16
	v_lshl_add_u64 v[66:67], v[66:67], 2, s[18:19]
	global_load_dwordx4 v[66:69], v[66:67], off
	v_mad_i64_i32 v[84:85], s[38:39], v163, s51, v[158:159]
	v_mad_i64_i32 v[92:93], s[38:39], v196, s51, v[158:159]
	v_lshl_add_u64 v[84:85], v[84:85], 0, v[82:83]
	v_mad_i64_i32 v[90:91], s[38:39], v195, s51, v[158:159]
	v_lshl_add_u64 v[92:93], v[92:93], 0, v[82:83]
	v_mad_i64_i32 v[98:99], s[38:39], v197, s51, v[158:159]
	v_lshl_add_u64 v[90:91], v[90:91], 0, v[82:83]
	v_lshl_add_u64 v[108:109], v[98:99], 0, v[82:83]
	global_load_dwordx2 v[114:115], v[84:85], off
	global_load_dwordx2 v[100:101], v[90:91], off
	global_load_dwordx2 v[98:99], v[92:93], off
	s_nop 0
	global_load_dwordx2 v[92:93], v[108:109], off
	v_mad_i64_i32 v[90:91], s[38:39], v199, s51, v[158:159]
	v_mad_i64_i32 v[84:85], s[38:39], v198, s51, v[158:159]
	v_lshl_add_u64 v[108:109], v[90:91], 0, v[82:83]
	v_mad_i64_i32 v[90:91], s[38:39], v200, s51, v[158:159]
	v_lshl_add_u64 v[84:85], v[84:85], 0, v[82:83]
	v_lshl_add_u64 v[82:83], v[90:91], 0, v[82:83]
	global_load_dwordx2 v[90:91], v[84:85], off
	s_nop 0
	global_load_dwordx2 v[84:85], v[108:109], off
	s_nop 0
	global_load_dwordx2 v[82:83], v[82:83], off
	s_mov_b64 s[38:39], s[34:35]
	s_waitcnt vmcnt(0)
; __device__ __forceinline__ unsigned cvt_pk_bf16(float lo, float hi) { unsigned r; asm volatile("v_cvt_pk_bf16_f32 %0, %1, %2" : "=v"(r) : "v"(lo), "v"(hi)); return r; }
; DI float lo_f(unsigned w) { return __uint_as_float(w << 16); }
; DI float hi_f(unsigned w) { return __uint_as_float(w & 0xffff0000u); }
; DI float sigmoid_(float x) { return rcp_(1.f + __expf(-x)); }
;     DI void operator()(const f32x4 (&acc)[2][2][4][2], const Unit& u, int wr, int wc, int fr, int fq) const {
;     ...
;             for (int ai = 0; ai < 2; ++ai)
; #pragma unroll
;                 for (int m = 0; m < 4; ++m) { const int row = row0 + ai * 128 + m * 16; const bool first = (row & (SEQ_ - 1)) == 0;
;                     const u32x2 xw = xws[ai * 4 + m];
;                     const float xv[4] = {lo_f(xw.x), hi_f(xw.x), lo_f(xw.y), hi_f(xw.y)};
;                     float la[4], uu[4];
; #pragma unroll
;                     for (int j = 0; j < 4; ++j) { const float r = sigmoid_(acc[ai][0][m][n][j] + ba4[j]), ig = sigmoid_(acc[ai][1][m][n][j] + bx4[j]);
;                         la[j] = k4[j] * r; const float om = 1.f - __expf(2.f * la[j]); const float mult = first ? 1.f : __builtin_amdgcn_sqrtf(fmaxf(om, 0.f)); uu[j] = xv[j] * ig * mult; }
;                     u32x2 w1, w2;
;                     w1.x = pg8::cvt_pk_bf16(la[0], la[1]); w1.y = pg8::cvt_pk_bf16(la[2], la[3]);
;                     w2.x = pg8::cvt_pk_bf16(uu[0], uu[1]); w2.y = pg8::cvt_pk_bf16(uu[2], uu[3]);
;                     *(u32x2*)(LA + (size_t)row * ldla + c4) = w1; *(u32x2*)(U + (size_t)row * LRU + c4) = w2; }
	v_add_f32_e32 v59, v59, v75
	v_mul_f32_e32 v59, 0xbfb8aa3b, v59
	v_add_f32_e32 v62, v62, v70
	v_mul_f32_e32 v62, 0xbfb8aa3b, v62
	v_exp_f32_e32 v59, v59
	v_exp_f32_e32 v62, v62
	v_lshlrev_b32_e32 v108, 16, v106
	v_add_f32_e32 v60, v60, v76
	v_add_f32_e32 v59, 1.0, v59
	v_add_f32_e32 v62, 1.0, v62
	v_rcp_f32_e32 v59, v59
	v_rcp_f32_e32 v62, v62
	v_add_f32_e32 v58, v58, v74
	v_add_f32_e32 v63, v63, v71
	v_mul_f32_e32 v59, v67, v59
	v_mul_f32_e32 v62, v62, v108
	v_add_f32_e32 v108, v59, v59
	v_mul_f32_e32 v108, 0x3fb8aa3b, v108
	v_mul_f32_e32 v60, 0xbfb8aa3b, v60
	v_add_f32_e32 v61, v61, v77
	v_mul_f32_e32 v58, 0xbfb8aa3b, v58
	v_exp_f32_e32 v108, v108
	v_mul_f32_e32 v63, 0xbfb8aa3b, v63
	v_exp_f32_e32 v60, v60
	v_mul_f32_e32 v61, 0xbfb8aa3b, v61
	v_exp_f32_e32 v58, v58
	v_exp_f32_e32 v63, v63
	v_exp_f32_e32 v61, v61
	v_sub_f32_e32 v108, 1.0, v108
	v_add_f32_e32 v60, 1.0, v60
	v_add_f32_e32 v58, 1.0, v58
	v_max_f32_e32 v108, 0, v108
	v_add_f32_e32 v63, 1.0, v63
	v_rcp_f32_e32 v60, v60
	v_add_f32_e32 v61, 1.0, v61
	v_rcp_f32_e32 v58, v58
	v_sqrt_f32_e32 v108, v108
	v_rcp_f32_e32 v63, v63
	v_rcp_f32_e32 v61, v61
	v_and_b32_e32 v106, 0xffff0000, v106
	v_mul_f32_e32 v60, v68, v60
	v_mul_f32_e32 v58, v66, v58
	v_cndmask_b32_e64 v108, v108, 1.0, s[8:9]
	v_mul_f32_e32 v63, v63, v106
	v_add_f32_e32 v106, v60, v60
	v_mul_f32_e32 v61, v69, v61
	v_add_f32_e32 v109, v58, v58
	v_add_f32_e32 v64, v64, v72
	v_mul_f32_e32 v63, v63, v108
	v_mul_f32_e32 v106, 0x3fb8aa3b, v106
	v_add_f32_e32 v108, v61, v61
	v_mul_f32_e32 v109, 0x3fb8aa3b, v109
	v_mul_f32_e32 v64, 0xbfb8aa3b, v64
	v_exp_f32_e32 v106, v106
	v_add_f32_e32 v65, v65, v73
	v_mul_f32_e32 v108, 0x3fb8aa3b, v108
	v_exp_f32_e32 v109, v109
	v_exp_f32_e32 v64, v64
	v_mul_f32_e32 v65, 0xbfb8aa3b, v65
	v_exp_f32_e32 v108, v108
	v_add_f32_e32 v51, v51, v75
	v_exp_f32_e32 v65, v65
	v_add_f32_e32 v54, v54, v70
	v_mul_f32_e32 v51, 0xbfb8aa3b, v51
	v_mul_f32_e32 v54, 0xbfb8aa3b, v54
	v_exp_f32_e32 v51, v51
	v_sub_f32_e32 v106, 1.0, v106
	v_exp_f32_e32 v54, v54
	v_sub_f32_e32 v109, 1.0, v109
	v_add_f32_e32 v64, 1.0, v64
	v_max_f32_e32 v106, 0, v106
	v_sub_f32_e32 v108, 1.0, v108
	v_max_f32_e32 v109, 0, v109
	v_sqrt_f32_e32 v106, v106
	v_rcp_f32_e32 v64, v64
	v_add_f32_e32 v65, 1.0, v65
	v_max_f32_e32 v108, 0, v108
	v_sqrt_f32_e32 v109, v109
	v_sqrt_f32_e32 v108, v108
	v_rcp_f32_e32 v65, v65
	v_add_f32_e32 v51, 1.0, v51
	v_add_f32_e32 v54, 1.0, v54
	v_rcp_f32_e32 v51, v51
	v_lshlrev_b32_e32 v116, 16, v107
	v_rcp_f32_e32 v54, v54
	v_and_b32_e32 v107, 0xffff0000, v107
	v_cndmask_b32_e64 v106, v106, 1.0, s[8:9]
	v_mul_f32_e32 v64, v64, v116
	v_cndmask_b32_e64 v109, v109, 1.0, s[8:9]
	v_mul_f32_e32 v64, v64, v106
	v_cndmask_b32_e64 v106, v108, 1.0, s[8:9]
	v_mul_f32_e32 v65, v65, v107
	v_cvt_pk_bf16_f32 v58, v58, v59
	v_cvt_pk_bf16_f32 v59, v60, v61
	v_mul_f32_e32 v62, v109, v62
	v_mul_f32_e32 v65, v65, v106
	v_cvt_pk_bf16_f32 v60, v62, v63
	v_cvt_pk_bf16_f32 v61, v64, v65
	v_mov_b32_e32 v246, v214
	v_mov_b32_e32 v247, v215
	v_mov_b32_e32 v248, v58
	v_mov_b32_e32 v249, v59
	global_store_dwordx4 v[134:135], v[246:249], off
	v_mov_b32_e32 v250, v216
	v_mov_b32_e32 v251, v217
	v_mov_b32_e32 v252, v60
	v_mov_b32_e32 v253, v61
	global_store_dwordx4 v[136:137], v[250:253], off
	v_lshlrev_b32_e32 v58, 16, v114
	v_mul_f32_e32 v51, v67, v51
	v_add_f32_e32 v50, v50, v74
	v_mul_f32_e32 v54, v54, v58
	v_add_f32_e32 v55, v55, v71
	v_add_f32_e32 v58, v51, v51
	v_add_f32_e32 v52, v52, v76
	v_add_f32_e32 v53, v53, v77
	v_mul_f32_e32 v50, 0xbfb8aa3b, v50
	v_mul_f32_e32 v55, 0xbfb8aa3b, v55
	v_mul_f32_e32 v58, 0x3fb8aa3b, v58
	v_mul_f32_e32 v52, 0xbfb8aa3b, v52
	v_mul_f32_e32 v53, 0xbfb8aa3b, v53
	v_exp_f32_e32 v50, v50
	v_exp_f32_e32 v55, v55
	v_exp_f32_e32 v58, v58
	v_exp_f32_e32 v52, v52
	v_exp_f32_e32 v53, v53
	v_add_f32_e32 v50, 1.0, v50
	v_add_f32_e32 v55, 1.0, v55
	v_sub_f32_e32 v58, 1.0, v58
	v_add_f32_e32 v52, 1.0, v52
	v_add_f32_e32 v53, 1.0, v53
	v_rcp_f32_e32 v50, v50
	v_rcp_f32_e32 v55, v55
	v_max_f32_e32 v58, 0, v58
	v_rcp_f32_e32 v52, v52
	v_rcp_f32_e32 v53, v53
	v_sqrt_f32_e32 v58, v58
	v_and_b32_e32 v59, 0xffff0000, v114
	v_mul_f32_e32 v50, v66, v50
	v_mul_f32_e32 v55, v55, v59
	v_mul_f32_e32 v52, v68, v52
	v_mul_f32_e32 v53, v69, v53
	v_add_f32_e32 v61, v50, v50
	v_add_f32_e32 v56, v56, v72
	v_mul_f32_e32 v55, v58, v55
	v_add_f32_e32 v58, v52, v52
	v_add_f32_e32 v57, v57, v73
	v_add_f32_e32 v59, v53, v53
	v_mul_f32_e32 v61, 0x3fb8aa3b, v61
	v_mul_f32_e32 v56, 0xbfb8aa3b, v56
	v_mul_f32_e32 v58, 0x3fb8aa3b, v58
	v_mul_f32_e32 v57, 0xbfb8aa3b, v57
	v_mul_f32_e32 v59, 0x3fb8aa3b, v59
	v_add_f32_e32 v43, v43, v75
	v_exp_f32_e32 v61, v61
	v_exp_f32_e32 v56, v56
	v_exp_f32_e32 v58, v58
	v_exp_f32_e32 v57, v57
	v_exp_f32_e32 v59, v59
	v_add_f32_e32 v46, v46, v70
	v_mul_f32_e32 v43, 0xbfb8aa3b, v43
	v_mul_f32_e32 v46, 0xbfb8aa3b, v46
	v_exp_f32_e32 v43, v43
	v_exp_f32_e32 v46, v46
	v_sub_f32_e32 v61, 1.0, v61
	v_add_f32_e32 v56, 1.0, v56
	v_sub_f32_e32 v58, 1.0, v58
	v_add_f32_e32 v57, 1.0, v57
	v_sub_f32_e32 v59, 1.0, v59
	v_max_f32_e32 v61, 0, v61
	v_rcp_f32_e32 v56, v56
	v_max_f32_e32 v58, 0, v58
	v_rcp_f32_e32 v57, v57
	v_max_f32_e32 v59, 0, v59
	v_add_f32_e32 v43, 1.0, v43
	v_sqrt_f32_e32 v61, v61
	v_sqrt_f32_e32 v58, v58
	v_sqrt_f32_e32 v59, v59
	v_add_f32_e32 v46, 1.0, v46
	v_rcp_f32_e32 v43, v43
	v_rcp_f32_e32 v46, v46
	v_lshlrev_b32_e32 v60, 16, v115
	v_and_b32_e32 v62, 0xffff0000, v115
	v_mul_f32_e32 v56, v56, v60
	v_mul_f32_e32 v57, v57, v62
	v_cvt_pk_bf16_f32 v50, v50, v51
	v_cvt_pk_bf16_f32 v51, v52, v53
	v_mul_f32_e32 v54, v61, v54
	v_mul_f32_e32 v56, v56, v58
	v_mul_f32_e32 v57, v57, v59
	v_cvt_pk_bf16_f32 v52, v54, v55
; __device__ __forceinline__ unsigned cvt_pk_bf16(float lo, float hi) { unsigned r; asm volatile("v_cvt_pk_bf16_f32 %0, %1, %2" : "=v"(r) : "v"(lo), "v"(hi)); return r; }
; DI float lo_f(unsigned w) { return __uint_as_float(w << 16); }
; DI float hi_f(unsigned w) { return __uint_as_float(w & 0xffff0000u); }
; DI float sigmoid_(float x) { return rcp_(1.f + __expf(-x)); }
;     DI void operator()(const f32x4 (&acc)[2][2][4][2], const Unit& u, int wr, int wc, int fr, int fq) const {
;     ...
;             for (int ai = 0; ai < 2; ++ai)
; #pragma unroll
;                 for (int m = 0; m < 4; ++m) { const int row = row0 + ai * 128 + m * 16; const bool first = (row & (SEQ_ - 1)) == 0;
;                     const u32x2 xw = xws[ai * 4 + m];
;                     const float xv[4] = {lo_f(xw.x), hi_f(xw.x), lo_f(xw.y), hi_f(xw.y)};
;                     float la[4], uu[4];
; #pragma unroll
;                     for (int j = 0; j < 4; ++j) { const float r = sigmoid_(acc[ai][0][m][n][j] + ba4[j]), ig = sigmoid_(acc[ai][1][m][n][j] + bx4[j]);
;                         la[j] = k4[j] * r; const float om = 1.f - __expf(2.f * la[j]); const float mult = first ? 1.f : __builtin_amdgcn_sqrtf(fmaxf(om, 0.f)); uu[j] = xv[j] * ig * mult; }
;                     u32x2 w1, w2;
;                     w1.x = pg8::cvt_pk_bf16(la[0], la[1]); w1.y = pg8::cvt_pk_bf16(la[2], la[3]);
;                     w2.x = pg8::cvt_pk_bf16(uu[0], uu[1]); w2.y = pg8::cvt_pk_bf16(uu[2], uu[3]);
;                     *(u32x2*)(LA + (size_t)row * ldla + c4) = w1; *(u32x2*)(U + (size_t)row * LRU + c4) = w2; }
	v_cvt_pk_bf16_f32 v53, v56, v57
	v_mov_b32_e32 v246, v218
	v_mov_b32_e32 v247, v219
	v_mov_b32_e32 v248, v50
	v_mov_b32_e32 v249, v51
	global_store_dwordx4 v[126:127], v[246:249], off
	v_mov_b32_e32 v250, v220
	v_mov_b32_e32 v251, v221
	v_mov_b32_e32 v252, v52
	v_mov_b32_e32 v253, v53
	global_store_dwordx4 v[128:129], v[250:253], off
	v_lshlrev_b32_e32 v50, 16, v100
	v_mul_f32_e32 v43, v67, v43
	v_add_f32_e32 v42, v42, v74
	v_mul_f32_e32 v46, v46, v50
	v_add_f32_e32 v47, v47, v71
	v_add_f32_e32 v50, v43, v43
	v_add_f32_e32 v44, v44, v76
	v_add_f32_e32 v45, v45, v77
	v_mul_f32_e32 v42, 0xbfb8aa3b, v42
	v_mul_f32_e32 v47, 0xbfb8aa3b, v47
	v_mul_f32_e32 v50, 0x3fb8aa3b, v50
	v_mul_f32_e32 v44, 0xbfb8aa3b, v44
	v_mul_f32_e32 v45, 0xbfb8aa3b, v45
	v_exp_f32_e32 v42, v42
	v_exp_f32_e32 v47, v47
	v_exp_f32_e32 v50, v50
	v_exp_f32_e32 v44, v44
	v_exp_f32_e32 v45, v45
	v_add_f32_e32 v42, 1.0, v42
	v_add_f32_e32 v47, 1.0, v47
	v_sub_f32_e32 v50, 1.0, v50
	v_add_f32_e32 v44, 1.0, v44
	v_add_f32_e32 v45, 1.0, v45
	v_rcp_f32_e32 v42, v42
	v_rcp_f32_e32 v47, v47
	v_max_f32_e32 v50, 0, v50
	v_rcp_f32_e32 v44, v44
	v_rcp_f32_e32 v45, v45
	v_sqrt_f32_e32 v50, v50
	v_and_b32_e32 v51, 0xffff0000, v100
	v_mul_f32_e32 v42, v66, v42
	v_mul_f32_e32 v47, v47, v51
	v_mul_f32_e32 v44, v68, v44
	v_mul_f32_e32 v45, v69, v45
	v_add_f32_e32 v53, v42, v42
	v_add_f32_e32 v48, v48, v72
	v_mul_f32_e32 v47, v50, v47
	v_add_f32_e32 v50, v44, v44
	v_add_f32_e32 v49, v49, v73
	v_add_f32_e32 v51, v45, v45
	v_mul_f32_e32 v53, 0x3fb8aa3b, v53
	v_mul_f32_e32 v48, 0xbfb8aa3b, v48
	v_mul_f32_e32 v50, 0x3fb8aa3b, v50
	v_mul_f32_e32 v49, 0xbfb8aa3b, v49
	v_mul_f32_e32 v51, 0x3fb8aa3b, v51
	v_add_f32_e32 v35, v35, v75
	v_exp_f32_e32 v53, v53
	v_exp_f32_e32 v48, v48
	v_exp_f32_e32 v50, v50
	v_exp_f32_e32 v49, v49
	v_exp_f32_e32 v51, v51
	v_add_f32_e32 v38, v38, v70
	v_mul_f32_e32 v35, 0xbfb8aa3b, v35
	v_mul_f32_e32 v38, 0xbfb8aa3b, v38
	v_exp_f32_e32 v35, v35
	v_exp_f32_e32 v38, v38
	v_sub_f32_e32 v53, 1.0, v53
	v_add_f32_e32 v48, 1.0, v48
	v_sub_f32_e32 v50, 1.0, v50
	v_add_f32_e32 v49, 1.0, v49
	v_sub_f32_e32 v51, 1.0, v51
	v_max_f32_e32 v53, 0, v53
	v_rcp_f32_e32 v48, v48
	v_max_f32_e32 v50, 0, v50
	v_rcp_f32_e32 v49, v49
	v_max_f32_e32 v51, 0, v51
	v_add_f32_e32 v35, 1.0, v35
	v_sqrt_f32_e32 v53, v53
	v_sqrt_f32_e32 v50, v50
	v_sqrt_f32_e32 v51, v51
	v_add_f32_e32 v38, 1.0, v38
	v_rcp_f32_e32 v35, v35
	v_rcp_f32_e32 v38, v38
	v_lshlrev_b32_e32 v52, 16, v101
	v_and_b32_e32 v54, 0xffff0000, v101
	v_mul_f32_e32 v48, v48, v52
	v_mul_f32_e32 v49, v49, v54
	v_cvt_pk_bf16_f32 v42, v42, v43
	v_cvt_pk_bf16_f32 v43, v44, v45
	v_mul_f32_e32 v46, v53, v46
	v_mul_f32_e32 v48, v48, v50
	v_mul_f32_e32 v49, v49, v51
	v_cvt_pk_bf16_f32 v44, v46, v47
	v_cvt_pk_bf16_f32 v45, v48, v49
	v_mov_b32_e32 v246, v222
	v_mov_b32_e32 v247, v223
	v_mov_b32_e32 v248, v42
	v_mov_b32_e32 v249, v43
	global_store_dwordx4 v[118:119], v[246:249], off
	v_mov_b32_e32 v250, v224
	v_mov_b32_e32 v251, v225
	v_mov_b32_e32 v252, v44
	v_mov_b32_e32 v253, v45
	global_store_dwordx4 v[120:121], v[250:253], off
	v_lshlrev_b32_e32 v42, 16, v98
	v_mul_f32_e32 v35, v67, v35
	v_add_f32_e32 v34, v34, v74
	v_mul_f32_e32 v38, v38, v42
	v_add_f32_e32 v39, v39, v71
	v_add_f32_e32 v42, v35, v35
	v_add_f32_e32 v36, v36, v76
	v_add_f32_e32 v37, v37, v77
	v_mul_f32_e32 v34, 0xbfb8aa3b, v34
	v_mul_f32_e32 v39, 0xbfb8aa3b, v39
	v_mul_f32_e32 v42, 0x3fb8aa3b, v42
	v_mul_f32_e32 v36, 0xbfb8aa3b, v36
	v_mul_f32_e32 v37, 0xbfb8aa3b, v37
	v_exp_f32_e32 v34, v34
	v_exp_f32_e32 v39, v39
	v_exp_f32_e32 v42, v42
	v_exp_f32_e32 v36, v36
	v_exp_f32_e32 v37, v37
	v_add_f32_e32 v34, 1.0, v34
	v_add_f32_e32 v39, 1.0, v39
	v_sub_f32_e32 v42, 1.0, v42
	v_add_f32_e32 v36, 1.0, v36
	v_add_f32_e32 v37, 1.0, v37
	v_rcp_f32_e32 v34, v34
	v_rcp_f32_e32 v39, v39
	v_max_f32_e32 v42, 0, v42
	v_rcp_f32_e32 v36, v36
	v_rcp_f32_e32 v37, v37
	v_sqrt_f32_e32 v42, v42
	v_and_b32_e32 v43, 0xffff0000, v98
	v_mul_f32_e32 v34, v66, v34
	v_mul_f32_e32 v39, v39, v43
	v_mul_f32_e32 v36, v68, v36
	v_mul_f32_e32 v37, v69, v37
	v_add_f32_e32 v45, v34, v34
	v_add_f32_e32 v40, v40, v72
	v_mul_f32_e32 v39, v42, v39
	v_add_f32_e32 v42, v36, v36
	v_add_f32_e32 v41, v41, v73
	v_add_f32_e32 v43, v37, v37
	v_mul_f32_e32 v45, 0x3fb8aa3b, v45
	v_mul_f32_e32 v40, 0xbfb8aa3b, v40
	v_mul_f32_e32 v42, 0x3fb8aa3b, v42
	v_mul_f32_e32 v41, 0xbfb8aa3b, v41
	v_mul_f32_e32 v43, 0x3fb8aa3b, v43
	v_add_f32_e32 v27, v27, v75
	v_exp_f32_e32 v45, v45
	v_exp_f32_e32 v40, v40
	v_exp_f32_e32 v42, v42
	v_exp_f32_e32 v41, v41
	v_exp_f32_e32 v43, v43
	v_add_f32_e32 v30, v30, v70
	v_mul_f32_e32 v27, 0xbfb8aa3b, v27
	v_mul_f32_e32 v30, 0xbfb8aa3b, v30
	v_exp_f32_e32 v27, v27
	v_exp_f32_e32 v30, v30
	v_sub_f32_e32 v45, 1.0, v45
	v_add_f32_e32 v40, 1.0, v40
	v_sub_f32_e32 v42, 1.0, v42
	v_add_f32_e32 v41, 1.0, v41
	v_sub_f32_e32 v43, 1.0, v43
	v_max_f32_e32 v45, 0, v45
	v_rcp_f32_e32 v40, v40
	v_max_f32_e32 v42, 0, v42
	v_rcp_f32_e32 v41, v41
	v_max_f32_e32 v43, 0, v43
	v_add_f32_e32 v27, 1.0, v27
	v_sqrt_f32_e32 v45, v45
	v_sqrt_f32_e32 v42, v42
	v_sqrt_f32_e32 v43, v43
	v_add_f32_e32 v30, 1.0, v30
	v_rcp_f32_e32 v27, v27
	v_rcp_f32_e32 v30, v30
	v_lshlrev_b32_e32 v44, 16, v99
	v_and_b32_e32 v46, 0xffff0000, v99
	v_mul_f32_e32 v40, v40, v44
	v_mul_f32_e32 v41, v41, v46
	v_cvt_pk_bf16_f32 v34, v34, v35
	v_mul_f32_e32 v38, v45, v38
	v_mul_f32_e32 v40, v40, v42
	v_mul_f32_e32 v41, v41, v43
	v_cvt_pk_bf16_f32 v35, v36, v37
	v_cvt_pk_bf16_f32 v36, v38, v39
	v_cvt_pk_bf16_f32 v37, v40, v41
	v_mov_b32_e32 v246, v226
	v_mov_b32_e32 v247, v227
	v_mov_b32_e32 v248, v34
	v_mov_b32_e32 v249, v35
	global_store_dwordx4 v[112:113], v[246:249], off
; __device__ __forceinline__ unsigned cvt_pk_bf16(float lo, float hi) { unsigned r; asm volatile("v_cvt_pk_bf16_f32 %0, %1, %2" : "=v"(r) : "v"(lo), "v"(hi)); return r; }
; DI float lo_f(unsigned w) { return __uint_as_float(w << 16); }
; DI float hi_f(unsigned w) { return __uint_as_float(w & 0xffff0000u); }
; DI float sigmoid_(float x) { return rcp_(1.f + __expf(-x)); }
;     DI void operator()(const f32x4 (&acc)[2][2][4][2], const Unit& u, int wr, int wc, int fr, int fq) const {
;     ...
;                 for (int m = 0; m < 4; ++m) { const int row = row0 + ai * 128 + m * 16; const bool first = (row & (SEQ_ - 1)) == 0;
;                     const u32x2 xw = xws[ai * 4 + m];
;                     const float xv[4] = {lo_f(xw.x), hi_f(xw.x), lo_f(xw.y), hi_f(xw.y)};
;                     float la[4], uu[4];
; #pragma unroll
;                     for (int j = 0; j < 4; ++j) { const float r = sigmoid_(acc[ai][0][m][n][j] + ba4[j]), ig = sigmoid_(acc[ai][1][m][n][j] + bx4[j]);
;                         la[j] = k4[j] * r; const float om = 1.f - __expf(2.f * la[j]); const float mult = first ? 1.f : __builtin_amdgcn_sqrtf(fmaxf(om, 0.f)); uu[j] = xv[j] * ig * mult; }
;                     u32x2 w1, w2;
;                     w1.x = pg8::cvt_pk_bf16(la[0], la[1]); w1.y = pg8::cvt_pk_bf16(la[2], la[3]);
;                     w2.x = pg8::cvt_pk_bf16(uu[0], uu[1]); w2.y = pg8::cvt_pk_bf16(uu[2], uu[3]);
;                     *(u32x2*)(LA + (size_t)row * ldla + c4) = w1; *(u32x2*)(U + (size_t)row * LRU + c4) = w2; }
	v_lshlrev_b32_e32 v34, 16, v92
	v_mul_f32_e32 v27, v67, v27
	v_mul_f32_e32 v30, v30, v34
	v_add_f32_e32 v34, v27, v27
	v_mul_f32_e32 v34, 0x3fb8aa3b, v34
	v_add_f32_e32 v31, v31, v71
	v_add_f32_e32 v28, v28, v76
	v_add_f32_e32 v26, v26, v74
	v_exp_f32_e32 v34, v34
	v_mul_f32_e32 v31, 0xbfb8aa3b, v31
	v_mul_f32_e32 v28, 0xbfb8aa3b, v28
	v_add_f32_e32 v29, v29, v77
	v_mul_f32_e32 v26, 0xbfb8aa3b, v26
	v_exp_f32_e32 v31, v31
	v_exp_f32_e32 v28, v28
	v_mul_f32_e32 v29, 0xbfb8aa3b, v29
	v_exp_f32_e32 v26, v26
	v_exp_f32_e32 v29, v29
	v_sub_f32_e32 v34, 1.0, v34
	v_max_f32_e32 v34, 0, v34
	v_add_f32_e32 v31, 1.0, v31
	v_add_f32_e32 v28, 1.0, v28
	v_add_f32_e32 v26, 1.0, v26
	v_sqrt_f32_e32 v34, v34
	v_rcp_f32_e32 v31, v31
	v_rcp_f32_e32 v28, v28
	v_add_f32_e32 v29, 1.0, v29
	v_rcp_f32_e32 v26, v26
	v_rcp_f32_e32 v29, v29
	v_and_b32_e32 v35, 0xffff0000, v92
	v_cndmask_b32_e64 v34, v34, 1.0, vcc
	v_mul_f32_e32 v31, v31, v35
	v_mul_f32_e32 v28, v68, v28
	v_mul_f32_e32 v26, v66, v26
	v_mul_f32_e32 v31, v34, v31
	v_add_f32_e32 v34, v28, v28
	v_mul_f32_e32 v29, v69, v29
	v_mov_b32_e32 v250, v228
	v_mov_b32_e32 v251, v229
	v_mov_b32_e32 v252, v36
	v_mov_b32_e32 v253, v37
	global_store_dwordx4 v[110:111], v[250:253], off
	v_add_f32_e32 v36, v26, v26
	v_add_f32_e32 v32, v32, v72
	v_mul_f32_e32 v34, 0x3fb8aa3b, v34
	v_add_f32_e32 v35, v29, v29
	v_mul_f32_e32 v36, 0x3fb8aa3b, v36
	v_mul_f32_e32 v32, 0xbfb8aa3b, v32
	v_exp_f32_e32 v34, v34
	v_add_f32_e32 v33, v33, v73
	v_mul_f32_e32 v35, 0x3fb8aa3b, v35
	v_exp_f32_e32 v36, v36
	v_exp_f32_e32 v32, v32
	v_mul_f32_e32 v33, 0xbfb8aa3b, v33
	v_exp_f32_e32 v35, v35
	v_add_f32_e32 v19, v19, v75
	v_exp_f32_e32 v33, v33
	v_add_f32_e32 v22, v22, v70
	v_mul_f32_e32 v19, 0xbfb8aa3b, v19
	v_mul_f32_e32 v22, 0xbfb8aa3b, v22
	v_exp_f32_e32 v19, v19
	v_sub_f32_e32 v34, 1.0, v34
	v_exp_f32_e32 v22, v22
	v_sub_f32_e32 v36, 1.0, v36
	v_add_f32_e32 v32, 1.0, v32
	v_max_f32_e32 v34, 0, v34
	v_sub_f32_e32 v35, 1.0, v35
	v_max_f32_e32 v36, 0, v36
	v_sqrt_f32_e32 v34, v34
	v_rcp_f32_e32 v32, v32
	v_add_f32_e32 v33, 1.0, v33
	v_max_f32_e32 v35, 0, v35
	v_sqrt_f32_e32 v36, v36
	v_sqrt_f32_e32 v35, v35
	v_rcp_f32_e32 v33, v33
	v_add_f32_e32 v19, 1.0, v19
	v_add_f32_e32 v22, 1.0, v22
	v_rcp_f32_e32 v19, v19
	v_lshlrev_b32_e32 v37, 16, v93
	v_rcp_f32_e32 v22, v22
	v_and_b32_e32 v38, 0xffff0000, v93
	v_cndmask_b32_e64 v34, v34, 1.0, vcc
	v_mul_f32_e32 v32, v32, v37
	v_cndmask_b32_e64 v36, v36, 1.0, vcc
	v_mul_f32_e32 v32, v32, v34
	v_cndmask_b32_e64 v34, v35, 1.0, vcc
	v_mul_f32_e32 v33, v33, v38
	v_cvt_pk_bf16_f32 v26, v26, v27
	v_cvt_pk_bf16_f32 v27, v28, v29
	v_mul_f32_e32 v30, v36, v30
	v_mul_f32_e32 v33, v33, v34
	v_cvt_pk_bf16_f32 v28, v30, v31
	v_cvt_pk_bf16_f32 v29, v32, v33
	v_mov_b32_e32 v246, v230
	v_mov_b32_e32 v247, v231
	v_mov_b32_e32 v248, v26
	v_mov_b32_e32 v249, v27
	global_store_dwordx4 v[102:103], v[246:249], off
	v_mov_b32_e32 v250, v232
	v_mov_b32_e32 v251, v233
	v_mov_b32_e32 v252, v28
	v_mov_b32_e32 v253, v29
	global_store_dwordx4 v[104:105], v[250:253], off
	v_lshlrev_b32_e32 v26, 16, v90
	v_mul_f32_e32 v19, v67, v19
	v_add_f32_e32 v18, v18, v74
	v_mul_f32_e32 v22, v22, v26
	v_add_f32_e32 v23, v23, v71
	v_add_f32_e32 v26, v19, v19
	v_add_f32_e32 v20, v20, v76
	v_add_f32_e32 v21, v21, v77
	v_mul_f32_e32 v18, 0xbfb8aa3b, v18
	v_mul_f32_e32 v23, 0xbfb8aa3b, v23
	v_mul_f32_e32 v26, 0x3fb8aa3b, v26
	v_mul_f32_e32 v20, 0xbfb8aa3b, v20
	v_mul_f32_e32 v21, 0xbfb8aa3b, v21
	v_exp_f32_e32 v18, v18
	v_exp_f32_e32 v23, v23
	v_exp_f32_e32 v26, v26
	v_exp_f32_e32 v20, v20
	v_exp_f32_e32 v21, v21
	v_add_f32_e32 v18, 1.0, v18
	v_add_f32_e32 v23, 1.0, v23
	v_sub_f32_e32 v26, 1.0, v26
	v_add_f32_e32 v20, 1.0, v20
	v_add_f32_e32 v21, 1.0, v21
	v_rcp_f32_e32 v18, v18
	v_rcp_f32_e32 v23, v23
	v_max_f32_e32 v26, 0, v26
	v_rcp_f32_e32 v20, v20
	v_rcp_f32_e32 v21, v21
	v_sqrt_f32_e32 v26, v26
	v_and_b32_e32 v27, 0xffff0000, v90
	v_mul_f32_e32 v18, v66, v18
	v_mul_f32_e32 v23, v23, v27
	v_mul_f32_e32 v20, v68, v20
	v_mul_f32_e32 v21, v69, v21
	v_add_f32_e32 v29, v18, v18
	v_add_f32_e32 v24, v24, v72
	v_mul_f32_e32 v23, v26, v23
	v_add_f32_e32 v26, v20, v20
	v_add_f32_e32 v25, v25, v73
	v_add_f32_e32 v27, v21, v21
	v_mul_f32_e32 v29, 0x3fb8aa3b, v29
	v_mul_f32_e32 v24, 0xbfb8aa3b, v24
	v_mul_f32_e32 v26, 0x3fb8aa3b, v26
	v_mul_f32_e32 v25, 0xbfb8aa3b, v25
	v_mul_f32_e32 v27, 0x3fb8aa3b, v27
	v_add_f32_e32 v11, v11, v75
	v_exp_f32_e32 v29, v29
	v_exp_f32_e32 v24, v24
	v_exp_f32_e32 v26, v26
	v_exp_f32_e32 v25, v25
	v_exp_f32_e32 v27, v27
	v_add_f32_e32 v14, v14, v70
	v_mul_f32_e32 v11, 0xbfb8aa3b, v11
	v_mul_f32_e32 v14, 0xbfb8aa3b, v14
	v_exp_f32_e32 v11, v11
	v_exp_f32_e32 v14, v14
	v_sub_f32_e32 v29, 1.0, v29
	v_add_f32_e32 v24, 1.0, v24
	v_sub_f32_e32 v26, 1.0, v26
	v_add_f32_e32 v25, 1.0, v25
	v_sub_f32_e32 v27, 1.0, v27
	v_max_f32_e32 v29, 0, v29
	v_rcp_f32_e32 v24, v24
	v_max_f32_e32 v26, 0, v26
	v_rcp_f32_e32 v25, v25
	v_max_f32_e32 v27, 0, v27
	v_add_f32_e32 v11, 1.0, v11
	v_sqrt_f32_e32 v29, v29
	v_sqrt_f32_e32 v26, v26
	v_sqrt_f32_e32 v27, v27
	v_add_f32_e32 v14, 1.0, v14
	v_rcp_f32_e32 v11, v11
	v_rcp_f32_e32 v14, v14
	v_lshlrev_b32_e32 v28, 16, v91
	v_and_b32_e32 v30, 0xffff0000, v91
	v_mul_f32_e32 v24, v24, v28
	v_mul_f32_e32 v25, v25, v30
	v_cvt_pk_bf16_f32 v18, v18, v19
	v_cvt_pk_bf16_f32 v19, v20, v21
	v_mul_f32_e32 v22, v29, v22
	v_mul_f32_e32 v24, v26, v24
	v_mul_f32_e32 v25, v25, v27
	v_cvt_pk_bf16_f32 v20, v22, v23
; __device__ __forceinline__ unsigned cvt_pk_bf16(float lo, float hi) { unsigned r; asm volatile("v_cvt_pk_bf16_f32 %0, %1, %2" : "=v"(r) : "v"(lo), "v"(hi)); return r; }
; DI float lo_f(unsigned w) { return __uint_as_float(w << 16); }
; DI float hi_f(unsigned w) { return __uint_as_float(w & 0xffff0000u); }
; DI float sigmoid_(float x) { return rcp_(1.f + __expf(-x)); }
;     DI void operator()(const f32x4 (&acc)[2][2][4][2], const Unit& u, int wr, int wc, int fr, int fq) const {
;     ...
;                 for (int m = 0; m < 4; ++m) { const int row = row0 + ai * 128 + m * 16; const bool first = (row & (SEQ_ - 1)) == 0;
;                     const u32x2 xw = xws[ai * 4 + m];
;                     const float xv[4] = {lo_f(xw.x), hi_f(xw.x), lo_f(xw.y), hi_f(xw.y)};
;                     float la[4], uu[4];
; #pragma unroll
;                     for (int j = 0; j < 4; ++j) { const float r = sigmoid_(acc[ai][0][m][n][j] + ba4[j]), ig = sigmoid_(acc[ai][1][m][n][j] + bx4[j]);
;                         la[j] = k4[j] * r; const float om = 1.f - __expf(2.f * la[j]); const float mult = first ? 1.f : __builtin_amdgcn_sqrtf(fmaxf(om, 0.f)); uu[j] = xv[j] * ig * mult; }
;                     u32x2 w1, w2;
;                     w1.x = pg8::cvt_pk_bf16(la[0], la[1]); w1.y = pg8::cvt_pk_bf16(la[2], la[3]);
;                     w2.x = pg8::cvt_pk_bf16(uu[0], uu[1]); w2.y = pg8::cvt_pk_bf16(uu[2], uu[3]);
;                     *(u32x2*)(LA + (size_t)row * ldla + c4) = w1; *(u32x2*)(U + (size_t)row * LRU + c4) = w2; }
;             asm volatile("" ::: "memory");
;         }
;     }
	v_cvt_pk_bf16_f32 v21, v24, v25
	v_mov_b32_e32 v246, v234
	v_mov_b32_e32 v247, v235
	v_mov_b32_e32 v248, v18
	v_mov_b32_e32 v249, v19
	global_store_dwordx4 v[94:95], v[246:249], off
	v_mov_b32_e32 v250, v236
	v_mov_b32_e32 v251, v237
	v_mov_b32_e32 v252, v20
	v_mov_b32_e32 v253, v21
	global_store_dwordx4 v[96:97], v[250:253], off
	v_lshlrev_b32_e32 v18, 16, v84
	v_mul_f32_e32 v11, v67, v11
	v_add_f32_e32 v10, v10, v74
	v_mul_f32_e32 v14, v14, v18
	v_add_f32_e32 v15, v15, v71
	v_add_f32_e32 v18, v11, v11
	v_add_f32_e32 v12, v12, v76
	v_add_f32_e32 v13, v13, v77
	v_mul_f32_e32 v10, 0xbfb8aa3b, v10
	v_mul_f32_e32 v15, 0xbfb8aa3b, v15
	v_mul_f32_e32 v18, 0x3fb8aa3b, v18
	v_mul_f32_e32 v12, 0xbfb8aa3b, v12
	v_mul_f32_e32 v13, 0xbfb8aa3b, v13
	v_exp_f32_e32 v10, v10
	v_exp_f32_e32 v15, v15
	v_exp_f32_e32 v18, v18
	v_exp_f32_e32 v12, v12
	v_exp_f32_e32 v13, v13
	v_add_f32_e32 v10, 1.0, v10
	v_add_f32_e32 v15, 1.0, v15
	v_sub_f32_e32 v18, 1.0, v18
	v_add_f32_e32 v12, 1.0, v12
	v_add_f32_e32 v13, 1.0, v13
	v_rcp_f32_e32 v10, v10
	v_rcp_f32_e32 v15, v15
	v_max_f32_e32 v18, 0, v18
	v_rcp_f32_e32 v12, v12
	v_rcp_f32_e32 v13, v13
	v_sqrt_f32_e32 v18, v18
	v_and_b32_e32 v19, 0xffff0000, v84
	v_mul_f32_e32 v10, v66, v10
	v_mul_f32_e32 v15, v15, v19
	v_mul_f32_e32 v12, v68, v12
	v_mul_f32_e32 v13, v69, v13
	v_add_f32_e32 v21, v10, v10
	v_add_f32_e32 v16, v16, v72
	v_mul_f32_e32 v15, v18, v15
	v_add_f32_e32 v18, v12, v12
	v_add_f32_e32 v17, v17, v73
	v_add_f32_e32 v19, v13, v13
	v_mul_f32_e32 v21, 0x3fb8aa3b, v21
	v_mul_f32_e32 v16, 0xbfb8aa3b, v16
	v_mul_f32_e32 v18, 0x3fb8aa3b, v18
	v_mul_f32_e32 v17, 0xbfb8aa3b, v17
	v_mul_f32_e32 v19, 0x3fb8aa3b, v19
	v_add_f32_e32 v3, v3, v75
	v_exp_f32_e32 v21, v21
	v_exp_f32_e32 v16, v16
	v_exp_f32_e32 v18, v18
	v_exp_f32_e32 v17, v17
	v_exp_f32_e32 v19, v19
	v_add_f32_e32 v6, v6, v70
	v_mul_f32_e32 v3, 0xbfb8aa3b, v3
	v_mul_f32_e32 v6, 0xbfb8aa3b, v6
	v_exp_f32_e32 v3, v3
	v_exp_f32_e32 v6, v6
	v_sub_f32_e32 v21, 1.0, v21
	v_add_f32_e32 v16, 1.0, v16
	v_sub_f32_e32 v18, 1.0, v18
	v_add_f32_e32 v17, 1.0, v17
	v_sub_f32_e32 v19, 1.0, v19
	v_max_f32_e32 v21, 0, v21
	v_rcp_f32_e32 v16, v16
	v_max_f32_e32 v18, 0, v18
	v_rcp_f32_e32 v17, v17
	v_max_f32_e32 v19, 0, v19
	v_add_f32_e32 v3, 1.0, v3
	v_sqrt_f32_e32 v21, v21
	v_sqrt_f32_e32 v18, v18
	v_sqrt_f32_e32 v19, v19
	v_add_f32_e32 v6, 1.0, v6
	v_rcp_f32_e32 v3, v3
	v_rcp_f32_e32 v6, v6
	v_lshlrev_b32_e32 v20, 16, v85
	v_and_b32_e32 v22, 0xffff0000, v85
	v_mul_f32_e32 v16, v16, v20
	v_mul_f32_e32 v17, v17, v22
	v_cvt_pk_bf16_f32 v10, v10, v11
	v_cvt_pk_bf16_f32 v11, v12, v13
	v_mul_f32_e32 v14, v21, v14
	v_mul_f32_e32 v16, v18, v16
	v_mul_f32_e32 v17, v17, v19
	v_cvt_pk_bf16_f32 v12, v14, v15
	v_cvt_pk_bf16_f32 v13, v16, v17
	v_mov_b32_e32 v246, v238
	v_mov_b32_e32 v247, v239
	v_mov_b32_e32 v248, v10
	v_mov_b32_e32 v249, v11
	global_store_dwordx4 v[86:87], v[246:249], off
	v_mov_b32_e32 v250, v240
	v_mov_b32_e32 v251, v241
	v_mov_b32_e32 v252, v12
	v_mov_b32_e32 v253, v13
	global_store_dwordx4 v[88:89], v[250:253], off
	v_lshlrev_b32_e32 v10, 16, v82
	v_mul_f32_e32 v3, v67, v3
	v_add_f32_e32 v2, v2, v74
	v_mul_f32_e32 v6, v6, v10
	v_add_f32_e32 v7, v7, v71
	v_add_f32_e32 v10, v3, v3
	v_add_f32_e32 v4, v4, v76
	v_add_f32_e32 v5, v5, v77
	v_mul_f32_e32 v2, 0xbfb8aa3b, v2
	v_mul_f32_e32 v7, 0xbfb8aa3b, v7
	v_mul_f32_e32 v10, 0x3fb8aa3b, v10
	v_mul_f32_e32 v4, 0xbfb8aa3b, v4
	v_mul_f32_e32 v5, 0xbfb8aa3b, v5
	v_exp_f32_e32 v2, v2
	v_exp_f32_e32 v7, v7
	v_exp_f32_e32 v10, v10
	v_exp_f32_e32 v4, v4
	v_exp_f32_e32 v5, v5
	v_add_f32_e32 v2, 1.0, v2
	v_add_f32_e32 v7, 1.0, v7
	v_sub_f32_e32 v10, 1.0, v10
	v_add_f32_e32 v4, 1.0, v4
	v_add_f32_e32 v5, 1.0, v5
	v_rcp_f32_e32 v2, v2
	v_rcp_f32_e32 v7, v7
	v_max_f32_e32 v10, 0, v10
	v_rcp_f32_e32 v4, v4
	v_rcp_f32_e32 v5, v5
	v_sqrt_f32_e32 v10, v10
	v_and_b32_e32 v11, 0xffff0000, v82
	v_mul_f32_e32 v2, v66, v2
	v_mul_f32_e32 v7, v7, v11
	v_mul_f32_e32 v4, v68, v4
	v_mul_f32_e32 v5, v69, v5
	v_add_f32_e32 v13, v2, v2
	v_add_f32_e32 v8, v8, v72
	v_mul_f32_e32 v7, v10, v7
	v_add_f32_e32 v10, v4, v4
	v_add_f32_e32 v9, v9, v73
	v_add_f32_e32 v11, v5, v5
	v_mul_f32_e32 v13, 0x3fb8aa3b, v13
	v_mul_f32_e32 v8, 0xbfb8aa3b, v8
	v_mul_f32_e32 v10, 0x3fb8aa3b, v10
	v_mul_f32_e32 v9, 0xbfb8aa3b, v9
	v_mul_f32_e32 v11, 0x3fb8aa3b, v11
	v_exp_f32_e32 v13, v13
	v_exp_f32_e32 v8, v8
	v_exp_f32_e32 v10, v10
	v_exp_f32_e32 v9, v9
	v_exp_f32_e32 v11, v11
	v_sub_f32_e32 v13, 1.0, v13
	v_add_f32_e32 v8, 1.0, v8
	v_sub_f32_e32 v10, 1.0, v10
	v_add_f32_e32 v9, 1.0, v9
	v_sub_f32_e32 v11, 1.0, v11
	v_max_f32_e32 v13, 0, v13
	v_rcp_f32_e32 v8, v8
	v_max_f32_e32 v10, 0, v10
	v_rcp_f32_e32 v9, v9
	v_max_f32_e32 v11, 0, v11
	v_sqrt_f32_e32 v13, v13
	v_sqrt_f32_e32 v10, v10
	v_sqrt_f32_e32 v11, v11
	v_lshlrev_b32_e32 v12, 16, v83
	v_and_b32_e32 v14, 0xffff0000, v83
	v_mul_f32_e32 v8, v8, v12
	v_mul_f32_e32 v9, v9, v14
	v_cvt_pk_bf16_f32 v2, v2, v3
	v_cvt_pk_bf16_f32 v3, v4, v5
	v_mul_f32_e32 v6, v13, v6
	v_mul_f32_e32 v8, v10, v8
	v_mul_f32_e32 v9, v11, v9
	v_cvt_pk_bf16_f32 v4, v6, v7
	v_cvt_pk_bf16_f32 v5, v8, v9
	v_mov_b32_e32 v246, v242
	v_mov_b32_e32 v247, v243
	v_mov_b32_e32 v248, v2
	v_mov_b32_e32 v249, v3
	global_store_dwordx4 v[78:79], v[246:249], off
	v_mov_b32_e32 v250, v244
	v_mov_b32_e32 v251, v245
	v_mov_b32_e32 v252, v4
	v_mov_b32_e32 v253, v5
	global_store_dwordx4 v[80:81], v[250:253], off
	s_andn2_b64 vcc, exec, s[6:7]
	s_cbranch_vccz .LBB0_941
